# in-proj GEMM epilogues (EpiOddIn/EpiEvenIn): tile-uniform fast paths - scalar segment dispatch per column tile, stores as scalar base + lane offset + immediate; compiler's per-unit ladder kept only fo
# speedup vs baseline: 1.0358x; 1.0064x over previous
;     ...
;   for (int u = (int)((blockIdx.x + gridDim.x - blk_off) % gridDim.x); u < nwg; u += gridDim.x) {
;     ...
;     __syncthreads();
;   }
.Lepo_done:
	v_readlane_b32 s0, v250, 1
	s_add_i32 s27, s27, s0
	s_cmpk_gt_i32 s27, 0x29f
	s_barrier
	v_readlane_b32 s1, v250, 2
	s_cbranch_scc1 .LBB0_996

; DI void st_bf16x4(bf16_t* p, f32x4 v) { u32x2 o; o.x = pk2e(v[0], v[1]); o.y = pk2e(v[2], v[3]); *(u32x2*)p = o; }
; DI void st_tr4(bf16_t* p, size_t stride, f32x4 v) { p[0] = f2bf(v[0]); p[stride] = f2bf(v[1]); p[2 * stride] = f2bf(v[2]); p[3 * stride] = f2bf(v[3]); }
;   DI float rowscale(int row) const { const f32x4 a = *(const f32x4*)(ssp_in + (size_t)row * 8), b = *(const f32x4*)(ssp_in + (size_t)row * 8 + 4);
;     return rsqrtf((((a[0] + a[1]) + (a[2] + a[3])) + ((b[0] + b[1]) + (b[2] + b[3]))) * (1.f / D_) + EPS_); }
;   DI void one(int row, int c, f32x4 v) const {
;     const int b = row >> 12, t = row & 4095;
;     if (c < 2048) { const int h = c >> 7, d = c & 127; st_bf16x4((bf16_t*)(ws + O_NQ) + ((size_t)(b * 16 + h) * T_ + t) * 128 + d, v); }
;     else if (c < 5120) {
;       const int seg = (c - 2048) >> 9, cc = (c - 2048) & 511, g = cc >> 7, d = cc & 127;
;       if (seg == 3 || seg == 5) st_tr4((bf16_t*)(ws + (seg == 3 ? O_VST : O_VWT)) + (size_t)(b * 4 + g) * 128 * T_ + (size_t)(t >> 5) * 4096 + d * 32 + ((((t & 31) >> 2) ^ ((d >> 2) & 7)) << 2) + (t & 3), 32, v);
;       else { const size_t off = seg == 0 ? O_KC : seg == 1 ? O_VC : seg == 2 ? O_KS : O_KW;
;         st_bf16x4((bf16_t*)(ws + off) + ((size_t)(b * 4 + g) * T_ + t) * 128 + d, v); }
;     } else if (c < 5168) { *(f32x4*)((float*)(ws + O_GT) + (size_t)row * 48 + (c - 5120)) = v; }
.LBB0_452:
	v_mov_b32_e32 v148, v199
	s_add_i32 s9, s0, s20
	v_and_b32_e32 v149, 15, v148
	v_or_b32_e32 v142, s9, v149
	v_ashrrev_i32_e32 v143, 31, v142
	v_readlane_b32 s0, v253, 52
	v_lshlrev_b64 v[134:135], 5, v[142:143]
	v_readlane_b32 s1, v253, 53
	v_lshrrev_b32_e32 v152, 2, v148
	v_and_b32_e32 v155, 12, v152
	v_lshl_add_u64 v[138:139], s[0:1], 0, v[134:135]
	s_mov_b64 s[100:101], 0x1000
	v_lshl_add_u64 v[240:241], v[138:139], 0, s[100:101]
	global_load_dwordx4 v[162:165], v[240:241], off offset:-4096
	global_load_dwordx4 v[166:169], v[240:241], off offset:-4080
	global_load_dwordx4 v[170:173], v[240:241], off offset:-3584
	global_load_dwordx4 v[174:177], v[240:241], off offset:-3568
	global_load_dwordx4 v[178:181], v[240:241], off offset:-3072
	global_load_dwordx4 v[182:185], v[240:241], off offset:-3056
	global_load_dwordx4 v[200:203], v[240:241], off offset:-2560
	global_load_dwordx4 v[204:207], v[240:241], off offset:-2544
	global_load_dwordx4 v[208:211], v[240:241], off
	global_load_dwordx4 v[212:215], v[240:241], off offset:16
	global_load_dwordx4 v[216:219], v[240:241], off offset:512
	global_load_dwordx4 v[220:223], v[240:241], off offset:528
	global_load_dwordx4 v[224:227], v[240:241], off offset:1024
	global_load_dwordx4 v[228:231], v[240:241], off offset:1040
	global_load_dwordx4 v[232:235], v[240:241], off offset:1536
	global_load_dwordx4 v[236:239], v[240:241], off offset:1552
	s_lshr_b32 s100, s8, 8
	s_cmp_lt_u32 s100, 20
	s_cbranch_scc0 .Lepo_generic
	s_mov_b32 s10, s100
	s_waitcnt vmcnt(14)
	v_add_f32_e32 v162, v162, v163
	v_add_f32_e32 v164, v164, v165
	v_add_f32_e32 v166, v166, v167
	v_add_f32_e32 v168, v168, v169
	v_add_f32_e32 v162, v162, v164
	v_add_f32_e32 v166, v166, v168
	v_add_f32_e32 v162, v162, v166
	v_fmamk_f32 v162, v162, 0x3a000000, v249
	v_cmp_gt_f32_e32 vcc, s84, v162
	v_mul_f32_e32 v163, 0x4b800000, v162
	s_nop 0
	v_cndmask_b32_e32 v162, v162, v163, vcc
	v_rsq_f32_e32 v162, v162
	s_nop 0
	v_mul_f32_e32 v163, 0x45800000, v162
	v_cndmask_b32_e32 v134, v162, v163, vcc
	s_waitcnt vmcnt(12)
	v_add_f32_e32 v170, v170, v171
	v_add_f32_e32 v172, v172, v173
	v_add_f32_e32 v174, v174, v175
	v_add_f32_e32 v176, v176, v177
	v_add_f32_e32 v170, v170, v172
	v_add_f32_e32 v174, v174, v176
	v_add_f32_e32 v170, v170, v174
	v_fmamk_f32 v170, v170, 0x3a000000, v249
	v_cmp_gt_f32_e32 vcc, s84, v170
	v_mul_f32_e32 v171, 0x4b800000, v170
	s_nop 0
	v_cndmask_b32_e32 v170, v170, v171, vcc
	v_rsq_f32_e32 v170, v170
	s_nop 0
	v_mul_f32_e32 v171, 0x45800000, v170
	v_cndmask_b32_e32 v136, v170, v171, vcc
	s_waitcnt vmcnt(10)
	v_add_f32_e32 v178, v178, v179
	v_add_f32_e32 v180, v180, v181
	v_add_f32_e32 v182, v182, v183
	v_add_f32_e32 v184, v184, v185
	v_add_f32_e32 v178, v178, v180
	v_add_f32_e32 v182, v182, v184
	v_add_f32_e32 v178, v178, v182
	v_fmamk_f32 v178, v178, 0x3a000000, v249
	v_cmp_gt_f32_e32 vcc, s84, v178
	v_mul_f32_e32 v179, 0x4b800000, v178
	s_nop 0
	v_cndmask_b32_e32 v178, v178, v179, vcc
	v_rsq_f32_e32 v178, v178
	s_nop 0
	v_mul_f32_e32 v179, 0x45800000, v178
	v_cndmask_b32_e32 v138, v178, v179, vcc
	s_waitcnt vmcnt(8)
	v_add_f32_e32 v200, v200, v201
	v_add_f32_e32 v202, v202, v203
	v_add_f32_e32 v204, v204, v205
	v_add_f32_e32 v206, v206, v207
	v_add_f32_e32 v200, v200, v202
	v_add_f32_e32 v204, v204, v206
	v_add_f32_e32 v200, v200, v204
	v_fmamk_f32 v200, v200, 0x3a000000, v249
	v_cmp_gt_f32_e32 vcc, s84, v200
	v_mul_f32_e32 v201, 0x4b800000, v200
	s_nop 0
	v_cndmask_b32_e32 v200, v200, v201, vcc
	v_rsq_f32_e32 v200, v200
	s_nop 0
	v_mul_f32_e32 v201, 0x45800000, v200
	v_cndmask_b32_e32 v140, v200, v201, vcc
	s_waitcnt vmcnt(6)
	v_add_f32_e32 v208, v208, v209
	v_add_f32_e32 v210, v210, v211
	v_add_f32_e32 v212, v212, v213
	v_add_f32_e32 v214, v214, v215
	v_add_f32_e32 v208, v208, v210
	v_add_f32_e32 v212, v212, v214
	v_add_f32_e32 v208, v208, v212
	v_fmamk_f32 v208, v208, 0x3a000000, v249
	v_cmp_gt_f32_e32 vcc, s84, v208
	v_mul_f32_e32 v209, 0x4b800000, v208
	s_nop 0
	v_cndmask_b32_e32 v208, v208, v209, vcc
	v_rsq_f32_e32 v208, v208
	s_nop 0
	v_mul_f32_e32 v209, 0x45800000, v208
	v_cndmask_b32_e32 v142, v208, v209, vcc
	s_waitcnt vmcnt(4)
	v_add_f32_e32 v216, v216, v217
	v_add_f32_e32 v218, v218, v219
	v_add_f32_e32 v220, v220, v221
	v_add_f32_e32 v222, v222, v223
	v_add_f32_e32 v216, v216, v218
	v_add_f32_e32 v220, v220, v222
	v_add_f32_e32 v216, v216, v220
	v_fmamk_f32 v216, v216, 0x3a000000, v249
	v_cmp_gt_f32_e32 vcc, s84, v216
	v_mul_f32_e32 v217, 0x4b800000, v216
	s_nop 0
	v_cndmask_b32_e32 v216, v216, v217, vcc
	v_rsq_f32_e32 v216, v216
	s_nop 0
	v_mul_f32_e32 v217, 0x45800000, v216
	v_cndmask_b32_e32 v146, v216, v217, vcc
	s_waitcnt vmcnt(2)
	v_add_f32_e32 v224, v224, v225
	v_add_f32_e32 v226, v226, v227
	v_add_f32_e32 v228, v228, v229
	v_add_f32_e32 v230, v230, v231
	v_add_f32_e32 v224, v224, v226
	v_add_f32_e32 v228, v228, v230
	v_add_f32_e32 v224, v224, v228
	v_fmamk_f32 v224, v224, 0x3a000000, v249
	v_cmp_gt_f32_e32 vcc, s84, v224
	v_mul_f32_e32 v225, 0x4b800000, v224
	s_nop 0
	v_cndmask_b32_e32 v224, v224, v225, vcc
	v_rsq_f32_e32 v224, v224
	s_nop 0
	v_mul_f32_e32 v225, 0x45800000, v224
	v_cndmask_b32_e32 v150, v224, v225, vcc
	s_waitcnt vmcnt(0)
	v_add_f32_e32 v232, v232, v233
	v_add_f32_e32 v234, v234, v235
	v_add_f32_e32 v236, v236, v237
	v_add_f32_e32 v238, v238, v239
	v_add_f32_e32 v232, v232, v234
	v_add_f32_e32 v236, v236, v238
	v_add_f32_e32 v232, v232, v236
	v_fmamk_f32 v232, v232, 0x3a000000, v249
	v_cmp_gt_f32_e32 vcc, s84, v232
	v_mul_f32_e32 v233, 0x4b800000, v232
	s_nop 0
	v_cndmask_b32_e32 v232, v232, v233, vcc
	v_rsq_f32_e32 v232, v232
	s_nop 0
	v_mul_f32_e32 v233, 0x45800000, v232
	v_cndmask_b32_e32 v154, v232, v233, vcc
	v_and_b32_e32 v157, 15, v199
	v_bfe_u32 v158, v199, 4, 2
	v_readlane_b32 s30, v253, 48
	v_readlane_b32 s31, v253, 49
	s_and_b32 s9, s9, 0xffffff00
	s_lshr_b32 s11, s9, 12
	s_and_b32 s12, s9, 0xfff
	s_lshl_b32 s12, s12, 8
	s_cmp_lt_u32 s10, 8
	s_cbranch_scc1 .Lepo_q
	s_sub_u32 s13, s10, 8
	s_and_b32 s14, s13, 1
	s_lshl_b32 s14, s14, 1
	s_lshr_b32 s13, s13, 1
	s_mov_b32 s15, 0x27145000
	s_cmp_eq_u32 s13, 1
	s_cmov_b32 s15, 0x27955000
	s_cmp_eq_u32 s13, 2
	s_cmov_b32 s15, 0x28165000
	s_cmp_eq_u32 s13, 3
	s_cmov_b32 s15, 0x29165000
	s_cmp_eq_u32 s13, 4
	s_cmov_b32 s15, 0x28965000
	s_cmp_eq_u32 s13, 5
	s_cmov_b32 s15, 0x29965000
	s_lshl_b32 s16, s11, 2
	s_add_i32 s16, s16, s14
	s_lshl_b32 s16, s16, 20
	s_add_i32 s16, s16, s12
	s_add_u32 s16, s16, s15
	s_add_u32 s34, s30, s16
	s_addc_u32 s35, s31, 0
	s_cmp_eq_u32 s13, 3
	s_cbranch_scc1 .Lepo_d
	s_cmp_eq_u32 s13, 5
	s_cbranch_scc1 .Lepo_d
	s_branch .Lepo_a
; DI void st_bf16x4(bf16_t* p, f32x4 v) { u32x2 o; o.x = pk2e(v[0], v[1]); o.y = pk2e(v[2], v[3]); *(u32x2*)p = o; }
; DI void st_tr4(bf16_t* p, size_t stride, f32x4 v) { p[0] = f2bf(v[0]); p[stride] = f2bf(v[1]); p[2 * stride] = f2bf(v[2]); p[3 * stride] = f2bf(v[3]); }
;   DI float operator()(int row, int colbase, int fq, f32x4 v0, f32x4 v1) const { one(row, colbase + 4 * fq, v0); one(row, colbase + 16 + 4 * fq, v1); return 0.f; }
;   DI float operator()(int row, int colbase, int fq, f32x4 v0, f32x4 v1) const { one(row, colbase + 4 * fq, v0); one(row, colbase + 16 + 4 * fq, v1); return 0.f; }
;   DI float operator()(int row, int colbase, int fq, f32x4 v0, f32x4 v1) const { one(row, colbase + 4 * fq, v0); one(row, colbase + 16 + 4 * fq, v1); return 0.f; }
;   DI void one(int row, int c, f32x4 v) const {
;     ...
;     if (c < 2048) { const int h = c >> 7, d = c & 127; st_bf16x4((bf16_t*)(ws + O_NQ) + ((size_t)(b * 16 + h) * T_ + t) * 128 + d, v); }
;     else if (c < 5120) {
;       const int seg = (c - 2048) >> 9, cc = (c - 2048) & 511, g = cc >> 7, d = cc & 127;
;       if (seg == 3 || seg == 5) st_tr4((bf16_t*)(ws + (seg == 3 ? O_VST : O_VWT)) + (size_t)(b * 4 + g) * 128 * T_ + (size_t)(t >> 5) * 4096 + d * 32 + ((((t & 31) >> 2) ^ ((d >> 2) & 7)) << 2) + (t & 3), 32, v);
;       else { const size_t off = seg == 0 ? O_KC : seg == 1 ? O_VC : seg == 2 ? O_KS : O_KW;
;         st_bf16x4((bf16_t*)(ws + off) + ((size_t)(b * 4 + g) * T_ + t) * 128 + d, v); }
;   DI float operator()(int row, int colbase, int fq, f32x4 v0, f32x4 v1) const { one(row, colbase + 4 * fq, v0); one(row, colbase + 16 + 4 * fq, v1); return 0.f; }
.Lepo_q:
	s_lshl_b32 s16, s11, 4
	s_lshl_b32 s14, s10, 1
	s_add_i32 s16, s16, s14
	s_lshl_b32 s16, s16, 20
	s_add_i32 s16, s16, s12
	s_add_u32 s16, s16, 0x25145000
	s_add_u32 s34, s30, s16
	s_addc_u32 s35, s31, 0
.Lepo_a:
	v_lshlrev_b32_e32 v156, 8, v157
	v_lshl_add_u32 v156, v158, 3, v156
	s_lshl_b32 s17, s20, 8
	s_lshl_b32 s16, s21, 1
	s_add_i32 s17, s17, s16
	v_add_u32_e32 v156, s17, v156
	s_mov_b64 s[100:101], s[34:35]
	v_pk_mul_f32 v[126:127], v[126:127], v[134:135] op_sel_hi:[1,0]
	v_pk_mul_f32 v[128:129], v[128:129], v[134:135] op_sel_hi:[1,0]
	v_cvt_pk_bf16_f32 v126, v126, v127
	v_cvt_pk_bf16_f32 v127, v128, v129
	global_store_dwordx2 v156, v[126:127], s[100:101]
	v_pk_mul_f32 v[122:123], v[122:123], v[134:135] op_sel_hi:[1,0]
	v_pk_mul_f32 v[124:125], v[124:125], v[134:135] op_sel_hi:[1,0]
	v_cvt_pk_bf16_f32 v122, v122, v123
	v_cvt_pk_bf16_f32 v123, v124, v125
	global_store_dwordx2 v156, v[122:123], s[100:101] offset:32
	s_add_u32 s100, s34, 0x100000
	s_addc_u32 s101, s35, 0
	v_pk_mul_f32 v[118:119], v[118:119], v[134:135] op_sel_hi:[1,0]
	v_pk_mul_f32 v[120:121], v[120:121], v[134:135] op_sel_hi:[1,0]
	v_cvt_pk_bf16_f32 v118, v118, v119
	v_cvt_pk_bf16_f32 v119, v120, v121
	global_store_dwordx2 v156, v[118:119], s[100:101]
	v_pk_mul_f32 v[114:115], v[114:115], v[134:135] op_sel_hi:[1,0]
	v_pk_mul_f32 v[116:117], v[116:117], v[134:135] op_sel_hi:[1,0]
	v_cvt_pk_bf16_f32 v114, v114, v115
	v_cvt_pk_bf16_f32 v115, v116, v117
	global_store_dwordx2 v156, v[114:115], s[100:101] offset:32
	s_add_u32 s100, s34, 0x1000
	s_addc_u32 s101, s35, 0
	v_pk_mul_f32 v[110:111], v[110:111], v[136:137] op_sel_hi:[1,0]
	v_pk_mul_f32 v[112:113], v[112:113], v[136:137] op_sel_hi:[1,0]
	v_cvt_pk_bf16_f32 v110, v110, v111
	v_cvt_pk_bf16_f32 v111, v112, v113
	global_store_dwordx2 v156, v[110:111], s[100:101]
	v_pk_mul_f32 v[106:107], v[106:107], v[136:137] op_sel_hi:[1,0]
	v_pk_mul_f32 v[108:109], v[108:109], v[136:137] op_sel_hi:[1,0]
	v_cvt_pk_bf16_f32 v106, v106, v107
	v_cvt_pk_bf16_f32 v107, v108, v109
	global_store_dwordx2 v156, v[106:107], s[100:101] offset:32
	s_add_u32 s100, s34, 0x101000
	s_addc_u32 s101, s35, 0
	v_pk_mul_f32 v[102:103], v[102:103], v[136:137] op_sel_hi:[1,0]
	v_pk_mul_f32 v[104:105], v[104:105], v[136:137] op_sel_hi:[1,0]
	v_cvt_pk_bf16_f32 v102, v102, v103
	v_cvt_pk_bf16_f32 v103, v104, v105
	global_store_dwordx2 v156, v[102:103], s[100:101]
	v_pk_mul_f32 v[98:99], v[98:99], v[136:137] op_sel_hi:[1,0]
	v_pk_mul_f32 v[100:101], v[100:101], v[136:137] op_sel_hi:[1,0]
	v_cvt_pk_bf16_f32 v98, v98, v99
	v_cvt_pk_bf16_f32 v99, v100, v101
	global_store_dwordx2 v156, v[98:99], s[100:101] offset:32
	s_add_u32 s100, s34, 0x2000
	s_addc_u32 s101, s35, 0
	v_pk_mul_f32 v[94:95], v[94:95], v[138:139] op_sel_hi:[1,0]
	v_pk_mul_f32 v[96:97], v[96:97], v[138:139] op_sel_hi:[1,0]
	v_cvt_pk_bf16_f32 v94, v94, v95
	v_cvt_pk_bf16_f32 v95, v96, v97
	global_store_dwordx2 v156, v[94:95], s[100:101]
	v_pk_mul_f32 v[90:91], v[90:91], v[138:139] op_sel_hi:[1,0]
	v_pk_mul_f32 v[92:93], v[92:93], v[138:139] op_sel_hi:[1,0]
	v_cvt_pk_bf16_f32 v90, v90, v91
	v_cvt_pk_bf16_f32 v91, v92, v93
	global_store_dwordx2 v156, v[90:91], s[100:101] offset:32
	s_add_u32 s100, s34, 0x102000
	s_addc_u32 s101, s35, 0
	v_pk_mul_f32 v[86:87], v[86:87], v[138:139] op_sel_hi:[1,0]
	v_pk_mul_f32 v[88:89], v[88:89], v[138:139] op_sel_hi:[1,0]
	v_cvt_pk_bf16_f32 v86, v86, v87
	v_cvt_pk_bf16_f32 v87, v88, v89
	global_store_dwordx2 v156, v[86:87], s[100:101]
	v_pk_mul_f32 v[82:83], v[82:83], v[138:139] op_sel_hi:[1,0]
	v_pk_mul_f32 v[84:85], v[84:85], v[138:139] op_sel_hi:[1,0]
	v_cvt_pk_bf16_f32 v82, v82, v83
	v_cvt_pk_bf16_f32 v83, v84, v85
	global_store_dwordx2 v156, v[82:83], s[100:101] offset:32
	s_add_u32 s100, s34, 0x3000
	s_addc_u32 s101, s35, 0
	v_pk_mul_f32 v[78:79], v[78:79], v[140:141] op_sel_hi:[1,0]
	v_pk_mul_f32 v[80:81], v[80:81], v[140:141] op_sel_hi:[1,0]
	v_cvt_pk_bf16_f32 v78, v78, v79
	v_cvt_pk_bf16_f32 v79, v80, v81
	global_store_dwordx2 v156, v[78:79], s[100:101]
	v_pk_mul_f32 v[74:75], v[74:75], v[140:141] op_sel_hi:[1,0]
	v_pk_mul_f32 v[76:77], v[76:77], v[140:141] op_sel_hi:[1,0]
	v_cvt_pk_bf16_f32 v74, v74, v75
	v_cvt_pk_bf16_f32 v75, v76, v77
	global_store_dwordx2 v156, v[74:75], s[100:101] offset:32
	s_add_u32 s100, s34, 0x103000
	s_addc_u32 s101, s35, 0
	v_pk_mul_f32 v[70:71], v[70:71], v[140:141] op_sel_hi:[1,0]
	v_pk_mul_f32 v[72:73], v[72:73], v[140:141] op_sel_hi:[1,0]
	v_cvt_pk_bf16_f32 v70, v70, v71
	v_cvt_pk_bf16_f32 v71, v72, v73
	global_store_dwordx2 v156, v[70:71], s[100:101]
	v_pk_mul_f32 v[66:67], v[66:67], v[140:141] op_sel_hi:[1,0]
	v_pk_mul_f32 v[68:69], v[68:69], v[140:141] op_sel_hi:[1,0]
	v_cvt_pk_bf16_f32 v66, v66, v67
	v_cvt_pk_bf16_f32 v67, v68, v69
	global_store_dwordx2 v156, v[66:67], s[100:101] offset:32
	s_add_u32 s100, s34, 0x8000
	s_addc_u32 s101, s35, 0
	v_pk_mul_f32 v[62:63], v[62:63], v[142:143] op_sel_hi:[1,0]
	v_pk_mul_f32 v[64:65], v[64:65], v[142:143] op_sel_hi:[1,0]
	v_cvt_pk_bf16_f32 v62, v62, v63
	v_cvt_pk_bf16_f32 v63, v64, v65
	global_store_dwordx2 v156, v[62:63], s[100:101]
	v_pk_mul_f32 v[58:59], v[58:59], v[142:143] op_sel_hi:[1,0]
	v_pk_mul_f32 v[60:61], v[60:61], v[142:143] op_sel_hi:[1,0]
	v_cvt_pk_bf16_f32 v58, v58, v59
	v_cvt_pk_bf16_f32 v59, v60, v61
	global_store_dwordx2 v156, v[58:59], s[100:101] offset:32
	s_add_u32 s100, s34, 0x108000
	s_addc_u32 s101, s35, 0
	v_pk_mul_f32 v[54:55], v[54:55], v[142:143] op_sel_hi:[1,0]
	v_pk_mul_f32 v[56:57], v[56:57], v[142:143] op_sel_hi:[1,0]
	v_cvt_pk_bf16_f32 v54, v54, v55
	v_cvt_pk_bf16_f32 v55, v56, v57
	global_store_dwordx2 v156, v[54:55], s[100:101]
; DI bf16_t f2bf(float x) { return (bf16_t)(pk2(x, 0.f) & 0xffffu); }
;   DI float operator()(int row, int colbase, int fq, f32x4 v0, f32x4 v1) const { one(row, colbase + 4 * fq, v0); one(row, colbase + 16 + 4 * fq, v1); return 0.f; }
;   DI float operator()(int row, int colbase, int fq, f32x4 v0, f32x4 v1) const { one(row, colbase + 4 * fq, v0); one(row, colbase + 16 + 4 * fq, v1); return 0.f; }
;   DI float operator()(int row, int colbase, int fq, f32x4 v0, f32x4 v1) const { one(row, colbase + 4 * fq, v0); one(row, colbase + 16 + 4 * fq, v1); return 0.f; }
; DI void st_tr4(bf16_t* p, size_t stride, f32x4 v) { p[0] = f2bf(v[0]); p[stride] = f2bf(v[1]); p[2 * stride] = f2bf(v[2]); p[3 * stride] = f2bf(v[3]); }
;   DI void one(int row, int c, f32x4 v) const {
;     ...
;       if (seg == 3 || seg == 5) st_tr4((bf16_t*)(ws + (seg == 3 ? O_VST : O_VWT)) + (size_t)(b * 4 + g) * 128 * T_ + (size_t)(t >> 5) * 4096 + d * 32 + ((((t & 31) >> 2) ^ ((d >> 2) & 7)) << 2) + (t & 3), 32, v);
;   DI float operator()(int row, int colbase, int fq, f32x4 v0, f32x4 v1) const { one(row, colbase + 4 * fq, v0); one(row, colbase + 16 + 4 * fq, v1); return 0.f; }
	v_pk_mul_f32 v[50:51], v[50:51], v[142:143] op_sel_hi:[1,0]
	v_pk_mul_f32 v[52:53], v[52:53], v[142:143] op_sel_hi:[1,0]
	v_cvt_pk_bf16_f32 v50, v50, v51
	v_cvt_pk_bf16_f32 v51, v52, v53
	global_store_dwordx2 v156, v[50:51], s[100:101] offset:32
	s_add_u32 s100, s34, 0x9000
	s_addc_u32 s101, s35, 0
	v_pk_mul_f32 v[46:47], v[46:47], v[146:147] op_sel_hi:[1,0]
	v_pk_mul_f32 v[48:49], v[48:49], v[146:147] op_sel_hi:[1,0]
	v_cvt_pk_bf16_f32 v46, v46, v47
	v_cvt_pk_bf16_f32 v47, v48, v49
	global_store_dwordx2 v156, v[46:47], s[100:101]
	v_pk_mul_f32 v[42:43], v[42:43], v[146:147] op_sel_hi:[1,0]
	v_pk_mul_f32 v[44:45], v[44:45], v[146:147] op_sel_hi:[1,0]
	v_cvt_pk_bf16_f32 v42, v42, v43
	v_cvt_pk_bf16_f32 v43, v44, v45
	global_store_dwordx2 v156, v[42:43], s[100:101] offset:32
	s_add_u32 s100, s34, 0x109000
	s_addc_u32 s101, s35, 0
	v_pk_mul_f32 v[38:39], v[38:39], v[146:147] op_sel_hi:[1,0]
	v_pk_mul_f32 v[40:41], v[40:41], v[146:147] op_sel_hi:[1,0]
	v_cvt_pk_bf16_f32 v38, v38, v39
	v_cvt_pk_bf16_f32 v39, v40, v41
	global_store_dwordx2 v156, v[38:39], s[100:101]
	v_pk_mul_f32 v[34:35], v[34:35], v[146:147] op_sel_hi:[1,0]
	v_pk_mul_f32 v[36:37], v[36:37], v[146:147] op_sel_hi:[1,0]
	v_cvt_pk_bf16_f32 v34, v34, v35
	v_cvt_pk_bf16_f32 v35, v36, v37
	global_store_dwordx2 v156, v[34:35], s[100:101] offset:32
	s_add_u32 s100, s34, 0xa000
	s_addc_u32 s101, s35, 0
	v_pk_mul_f32 v[30:31], v[30:31], v[150:151] op_sel_hi:[1,0]
	v_pk_mul_f32 v[32:33], v[32:33], v[150:151] op_sel_hi:[1,0]
	v_cvt_pk_bf16_f32 v30, v30, v31
	v_cvt_pk_bf16_f32 v31, v32, v33
	global_store_dwordx2 v156, v[30:31], s[100:101]
	v_pk_mul_f32 v[26:27], v[26:27], v[150:151] op_sel_hi:[1,0]
	v_pk_mul_f32 v[28:29], v[28:29], v[150:151] op_sel_hi:[1,0]
	v_cvt_pk_bf16_f32 v26, v26, v27
	v_cvt_pk_bf16_f32 v27, v28, v29
	global_store_dwordx2 v156, v[26:27], s[100:101] offset:32
	s_add_u32 s100, s34, 0x10a000
	s_addc_u32 s101, s35, 0
	v_pk_mul_f32 v[22:23], v[22:23], v[150:151] op_sel_hi:[1,0]
	v_pk_mul_f32 v[24:25], v[24:25], v[150:151] op_sel_hi:[1,0]
	v_cvt_pk_bf16_f32 v22, v22, v23
	v_cvt_pk_bf16_f32 v23, v24, v25
	global_store_dwordx2 v156, v[22:23], s[100:101]
	v_pk_mul_f32 v[18:19], v[18:19], v[150:151] op_sel_hi:[1,0]
	v_pk_mul_f32 v[20:21], v[20:21], v[150:151] op_sel_hi:[1,0]
	v_cvt_pk_bf16_f32 v18, v18, v19
	v_cvt_pk_bf16_f32 v19, v20, v21
	global_store_dwordx2 v156, v[18:19], s[100:101] offset:32
	s_add_u32 s100, s34, 0xb000
	s_addc_u32 s101, s35, 0
	v_pk_mul_f32 v[14:15], v[14:15], v[154:155] op_sel_hi:[1,0]
	v_pk_mul_f32 v[16:17], v[16:17], v[154:155] op_sel_hi:[1,0]
	v_cvt_pk_bf16_f32 v14, v14, v15
	v_cvt_pk_bf16_f32 v15, v16, v17
	global_store_dwordx2 v156, v[14:15], s[100:101]
	v_pk_mul_f32 v[10:11], v[10:11], v[154:155] op_sel_hi:[1,0]
	v_pk_mul_f32 v[12:13], v[12:13], v[154:155] op_sel_hi:[1,0]
	v_cvt_pk_bf16_f32 v10, v10, v11
	v_cvt_pk_bf16_f32 v11, v12, v13
	global_store_dwordx2 v156, v[10:11], s[100:101] offset:32
	s_add_u32 s100, s34, 0x10b000
	s_addc_u32 s101, s35, 0
	v_pk_mul_f32 v[6:7], v[6:7], v[154:155] op_sel_hi:[1,0]
	v_pk_mul_f32 v[8:9], v[8:9], v[154:155] op_sel_hi:[1,0]
	v_cvt_pk_bf16_f32 v6, v6, v7
	v_cvt_pk_bf16_f32 v7, v8, v9
	global_store_dwordx2 v156, v[6:7], s[100:101]
	v_pk_mul_f32 v[2:3], v[2:3], v[154:155] op_sel_hi:[1,0]
	v_pk_mul_f32 v[4:5], v[4:5], v[154:155] op_sel_hi:[1,0]
	v_cvt_pk_bf16_f32 v2, v2, v3
	v_cvt_pk_bf16_f32 v3, v4, v5
	global_store_dwordx2 v156, v[2:3], s[100:101] offset:32
	s_branch .Lepo_done
.Lepo_d:
	v_lshrrev_b32_e32 v159, 2, v157
	v_xor_b32_e32 v159, v159, v158
	v_and_b32_e32 v156, 3, v157
	v_lshl_add_u32 v156, v159, 2, v156
	v_lshlrev_b32_e32 v156, 1, v156
	v_lshl_add_u32 v156, v158, 8, v156
	s_lshl_b32 s17, s20, 8
	s_lshl_b32 s16, s21, 6
	s_add_i32 s17, s17, s16
	v_add_u32_e32 v156, s17, v156
	s_mov_b64 s[100:101], s[34:35]
	v_pk_mul_f32 v[126:127], v[126:127], v[134:135] op_sel_hi:[1,0]
	v_pk_mul_f32 v[128:129], v[128:129], v[134:135] op_sel_hi:[1,0]
	v_cvt_pk_bf16_f32 v126, v126, v127
	v_cvt_pk_bf16_f32 v127, v128, v129
	global_store_short v156, v126, s[100:101]
	global_store_short_d16_hi v156, v126, s[100:101] offset:64
	global_store_short v156, v127, s[100:101] offset:128
	global_store_short_d16_hi v156, v127, s[100:101] offset:192
	v_pk_mul_f32 v[122:123], v[122:123], v[134:135] op_sel_hi:[1,0]
	v_pk_mul_f32 v[124:125], v[124:125], v[134:135] op_sel_hi:[1,0]
	v_cvt_pk_bf16_f32 v122, v122, v123
	v_cvt_pk_bf16_f32 v123, v124, v125
	global_store_short v156, v122, s[100:101] offset:1056
	global_store_short_d16_hi v156, v122, s[100:101] offset:1120
	global_store_short v156, v123, s[100:101] offset:1184
	global_store_short_d16_hi v156, v123, s[100:101] offset:1248
	s_add_u32 s100, s34, 0x100000
	s_addc_u32 s101, s35, 0
	v_pk_mul_f32 v[118:119], v[118:119], v[134:135] op_sel_hi:[1,0]
	v_pk_mul_f32 v[120:121], v[120:121], v[134:135] op_sel_hi:[1,0]
	v_cvt_pk_bf16_f32 v118, v118, v119
	v_cvt_pk_bf16_f32 v119, v120, v121
	global_store_short v156, v118, s[100:101]
	global_store_short_d16_hi v156, v118, s[100:101] offset:64
	global_store_short v156, v119, s[100:101] offset:128
	global_store_short_d16_hi v156, v119, s[100:101] offset:192
	v_pk_mul_f32 v[114:115], v[114:115], v[134:135] op_sel_hi:[1,0]
	v_pk_mul_f32 v[116:117], v[116:117], v[134:135] op_sel_hi:[1,0]
	v_cvt_pk_bf16_f32 v114, v114, v115
	v_cvt_pk_bf16_f32 v115, v116, v117
	global_store_short v156, v114, s[100:101] offset:1056
	global_store_short_d16_hi v156, v114, s[100:101] offset:1120
	global_store_short v156, v115, s[100:101] offset:1184
	global_store_short_d16_hi v156, v115, s[100:101] offset:1248
	s_mov_b64 s[100:101], s[34:35]
; DI bf16_t f2bf(float x) { return (bf16_t)(pk2(x, 0.f) & 0xffffu); }
; DI void st_tr4(bf16_t* p, size_t stride, f32x4 v) { p[0] = f2bf(v[0]); p[stride] = f2bf(v[1]); p[2 * stride] = f2bf(v[2]); p[3 * stride] = f2bf(v[3]); }
;   DI void one(int row, int c, f32x4 v) const {
;     ...
;       if (seg == 3 || seg == 5) st_tr4((bf16_t*)(ws + (seg == 3 ? O_VST : O_VWT)) + (size_t)(b * 4 + g) * 128 * T_ + (size_t)(t >> 5) * 4096 + d * 32 + ((((t & 31) >> 2) ^ ((d >> 2) & 7)) << 2) + (t & 3), 32, v);
	v_pk_mul_f32 v[110:111], v[110:111], v[136:137] op_sel_hi:[1,0]
	v_pk_mul_f32 v[112:113], v[112:113], v[136:137] op_sel_hi:[1,0]
	v_cvt_pk_bf16_f32 v110, v110, v111
	v_cvt_pk_bf16_f32 v111, v112, v113
	global_store_short v156, v110, s[100:101] offset:32
	global_store_short_d16_hi v156, v110, s[100:101] offset:96
	global_store_short v156, v111, s[100:101] offset:160
	global_store_short_d16_hi v156, v111, s[100:101] offset:224
	v_pk_mul_f32 v[106:107], v[106:107], v[136:137] op_sel_hi:[1,0]
	v_pk_mul_f32 v[108:109], v[108:109], v[136:137] op_sel_hi:[1,0]
	v_cvt_pk_bf16_f32 v106, v106, v107
	v_cvt_pk_bf16_f32 v107, v108, v109
	global_store_short v156, v106, s[100:101] offset:1024
	global_store_short_d16_hi v156, v106, s[100:101] offset:1088
	global_store_short v156, v107, s[100:101] offset:1152
	global_store_short_d16_hi v156, v107, s[100:101] offset:1216
	s_add_u32 s100, s34, 0x100000
	s_addc_u32 s101, s35, 0
	v_pk_mul_f32 v[102:103], v[102:103], v[136:137] op_sel_hi:[1,0]
	v_pk_mul_f32 v[104:105], v[104:105], v[136:137] op_sel_hi:[1,0]
	v_cvt_pk_bf16_f32 v102, v102, v103
	v_cvt_pk_bf16_f32 v103, v104, v105
	global_store_short v156, v102, s[100:101] offset:32
	global_store_short_d16_hi v156, v102, s[100:101] offset:96
	global_store_short v156, v103, s[100:101] offset:160
	global_store_short_d16_hi v156, v103, s[100:101] offset:224
	v_pk_mul_f32 v[98:99], v[98:99], v[136:137] op_sel_hi:[1,0]
	v_pk_mul_f32 v[100:101], v[100:101], v[136:137] op_sel_hi:[1,0]
	v_cvt_pk_bf16_f32 v98, v98, v99
	v_cvt_pk_bf16_f32 v99, v100, v101
	global_store_short v156, v98, s[100:101] offset:1024
	global_store_short_d16_hi v156, v98, s[100:101] offset:1088
	global_store_short v156, v99, s[100:101] offset:1152
	global_store_short_d16_hi v156, v99, s[100:101] offset:1216
	s_add_u32 s100, s34, 0x2000
	s_addc_u32 s101, s35, 0
	v_pk_mul_f32 v[94:95], v[94:95], v[138:139] op_sel_hi:[1,0]
	v_pk_mul_f32 v[96:97], v[96:97], v[138:139] op_sel_hi:[1,0]
	v_cvt_pk_bf16_f32 v94, v94, v95
	v_cvt_pk_bf16_f32 v95, v96, v97
	global_store_short v156, v94, s[100:101]
	global_store_short_d16_hi v156, v94, s[100:101] offset:64
	global_store_short v156, v95, s[100:101] offset:128
	global_store_short_d16_hi v156, v95, s[100:101] offset:192
	v_pk_mul_f32 v[90:91], v[90:91], v[138:139] op_sel_hi:[1,0]
	v_pk_mul_f32 v[92:93], v[92:93], v[138:139] op_sel_hi:[1,0]
	v_cvt_pk_bf16_f32 v90, v90, v91
	v_cvt_pk_bf16_f32 v91, v92, v93
	global_store_short v156, v90, s[100:101] offset:1056
	global_store_short_d16_hi v156, v90, s[100:101] offset:1120
	global_store_short v156, v91, s[100:101] offset:1184
	global_store_short_d16_hi v156, v91, s[100:101] offset:1248
	s_add_u32 s100, s34, 0x102000
	s_addc_u32 s101, s35, 0
	v_pk_mul_f32 v[86:87], v[86:87], v[138:139] op_sel_hi:[1,0]
	v_pk_mul_f32 v[88:89], v[88:89], v[138:139] op_sel_hi:[1,0]
	v_cvt_pk_bf16_f32 v86, v86, v87
	v_cvt_pk_bf16_f32 v87, v88, v89
	global_store_short v156, v86, s[100:101]
	global_store_short_d16_hi v156, v86, s[100:101] offset:64
	global_store_short v156, v87, s[100:101] offset:128
	global_store_short_d16_hi v156, v87, s[100:101] offset:192
	v_pk_mul_f32 v[82:83], v[82:83], v[138:139] op_sel_hi:[1,0]
	v_pk_mul_f32 v[84:85], v[84:85], v[138:139] op_sel_hi:[1,0]
	v_cvt_pk_bf16_f32 v82, v82, v83
	v_cvt_pk_bf16_f32 v83, v84, v85
	global_store_short v156, v82, s[100:101] offset:1056
	global_store_short_d16_hi v156, v82, s[100:101] offset:1120
	global_store_short v156, v83, s[100:101] offset:1184
	global_store_short_d16_hi v156, v83, s[100:101] offset:1248
	s_add_u32 s100, s34, 0x2000
	s_addc_u32 s101, s35, 0
	v_pk_mul_f32 v[78:79], v[78:79], v[140:141] op_sel_hi:[1,0]
	v_pk_mul_f32 v[80:81], v[80:81], v[140:141] op_sel_hi:[1,0]
	v_cvt_pk_bf16_f32 v78, v78, v79
	v_cvt_pk_bf16_f32 v79, v80, v81
	global_store_short v156, v78, s[100:101] offset:32
	global_store_short_d16_hi v156, v78, s[100:101] offset:96
	global_store_short v156, v79, s[100:101] offset:160
	global_store_short_d16_hi v156, v79, s[100:101] offset:224
	v_pk_mul_f32 v[74:75], v[74:75], v[140:141] op_sel_hi:[1,0]
	v_pk_mul_f32 v[76:77], v[76:77], v[140:141] op_sel_hi:[1,0]
	v_cvt_pk_bf16_f32 v74, v74, v75
	v_cvt_pk_bf16_f32 v75, v76, v77
	global_store_short v156, v74, s[100:101] offset:1024
	global_store_short_d16_hi v156, v74, s[100:101] offset:1088
	global_store_short v156, v75, s[100:101] offset:1152
	global_store_short_d16_hi v156, v75, s[100:101] offset:1216
	s_add_u32 s100, s34, 0x102000
	s_addc_u32 s101, s35, 0
	v_pk_mul_f32 v[70:71], v[70:71], v[140:141] op_sel_hi:[1,0]
	v_pk_mul_f32 v[72:73], v[72:73], v[140:141] op_sel_hi:[1,0]
	v_cvt_pk_bf16_f32 v70, v70, v71
	v_cvt_pk_bf16_f32 v71, v72, v73
	global_store_short v156, v70, s[100:101] offset:32
	global_store_short_d16_hi v156, v70, s[100:101] offset:96
	global_store_short v156, v71, s[100:101] offset:160
	global_store_short_d16_hi v156, v71, s[100:101] offset:224
	v_pk_mul_f32 v[66:67], v[66:67], v[140:141] op_sel_hi:[1,0]
	v_pk_mul_f32 v[68:69], v[68:69], v[140:141] op_sel_hi:[1,0]
	v_cvt_pk_bf16_f32 v66, v66, v67
	v_cvt_pk_bf16_f32 v67, v68, v69
	global_store_short v156, v66, s[100:101] offset:1024
	global_store_short_d16_hi v156, v66, s[100:101] offset:1088
	global_store_short v156, v67, s[100:101] offset:1152
	global_store_short_d16_hi v156, v67, s[100:101] offset:1216
	s_add_u32 s100, s34, 0x8000
	s_addc_u32 s101, s35, 0
	v_pk_mul_f32 v[62:63], v[62:63], v[142:143] op_sel_hi:[1,0]
	v_pk_mul_f32 v[64:65], v[64:65], v[142:143] op_sel_hi:[1,0]
	v_cvt_pk_bf16_f32 v62, v62, v63
	v_cvt_pk_bf16_f32 v63, v64, v65
	global_store_short v156, v62, s[100:101]
	global_store_short_d16_hi v156, v62, s[100:101] offset:64
; DI bf16_t f2bf(float x) { return (bf16_t)(pk2(x, 0.f) & 0xffffu); }
; DI void st_tr4(bf16_t* p, size_t stride, f32x4 v) { p[0] = f2bf(v[0]); p[stride] = f2bf(v[1]); p[2 * stride] = f2bf(v[2]); p[3 * stride] = f2bf(v[3]); }
;   DI void one(int row, int c, f32x4 v) const {
;     ...
;       if (seg == 3 || seg == 5) st_tr4((bf16_t*)(ws + (seg == 3 ? O_VST : O_VWT)) + (size_t)(b * 4 + g) * 128 * T_ + (size_t)(t >> 5) * 4096 + d * 32 + ((((t & 31) >> 2) ^ ((d >> 2) & 7)) << 2) + (t & 3), 32, v);
	global_store_short v156, v63, s[100:101] offset:128
	global_store_short_d16_hi v156, v63, s[100:101] offset:192
	v_pk_mul_f32 v[58:59], v[58:59], v[142:143] op_sel_hi:[1,0]
	v_pk_mul_f32 v[60:61], v[60:61], v[142:143] op_sel_hi:[1,0]
	v_cvt_pk_bf16_f32 v58, v58, v59
	v_cvt_pk_bf16_f32 v59, v60, v61
	global_store_short v156, v58, s[100:101] offset:1056
	global_store_short_d16_hi v156, v58, s[100:101] offset:1120
	global_store_short v156, v59, s[100:101] offset:1184
	global_store_short_d16_hi v156, v59, s[100:101] offset:1248
	s_add_u32 s100, s34, 0x108000
	s_addc_u32 s101, s35, 0
	v_pk_mul_f32 v[54:55], v[54:55], v[142:143] op_sel_hi:[1,0]
	v_pk_mul_f32 v[56:57], v[56:57], v[142:143] op_sel_hi:[1,0]
	v_cvt_pk_bf16_f32 v54, v54, v55
	v_cvt_pk_bf16_f32 v55, v56, v57
	global_store_short v156, v54, s[100:101]
	global_store_short_d16_hi v156, v54, s[100:101] offset:64
	global_store_short v156, v55, s[100:101] offset:128
	global_store_short_d16_hi v156, v55, s[100:101] offset:192
	v_pk_mul_f32 v[50:51], v[50:51], v[142:143] op_sel_hi:[1,0]
	v_pk_mul_f32 v[52:53], v[52:53], v[142:143] op_sel_hi:[1,0]
	v_cvt_pk_bf16_f32 v50, v50, v51
	v_cvt_pk_bf16_f32 v51, v52, v53
	global_store_short v156, v50, s[100:101] offset:1056
	global_store_short_d16_hi v156, v50, s[100:101] offset:1120
	global_store_short v156, v51, s[100:101] offset:1184
	global_store_short_d16_hi v156, v51, s[100:101] offset:1248
	s_add_u32 s100, s34, 0x8000
	s_addc_u32 s101, s35, 0
	v_pk_mul_f32 v[46:47], v[46:47], v[146:147] op_sel_hi:[1,0]
	v_pk_mul_f32 v[48:49], v[48:49], v[146:147] op_sel_hi:[1,0]
	v_cvt_pk_bf16_f32 v46, v46, v47
	v_cvt_pk_bf16_f32 v47, v48, v49
	global_store_short v156, v46, s[100:101] offset:32
	global_store_short_d16_hi v156, v46, s[100:101] offset:96
	global_store_short v156, v47, s[100:101] offset:160
	global_store_short_d16_hi v156, v47, s[100:101] offset:224
	v_pk_mul_f32 v[42:43], v[42:43], v[146:147] op_sel_hi:[1,0]
	v_pk_mul_f32 v[44:45], v[44:45], v[146:147] op_sel_hi:[1,0]
	v_cvt_pk_bf16_f32 v42, v42, v43
	v_cvt_pk_bf16_f32 v43, v44, v45
	global_store_short v156, v42, s[100:101] offset:1024
	global_store_short_d16_hi v156, v42, s[100:101] offset:1088
	global_store_short v156, v43, s[100:101] offset:1152
	global_store_short_d16_hi v156, v43, s[100:101] offset:1216
	s_add_u32 s100, s34, 0x108000
	s_addc_u32 s101, s35, 0
	v_pk_mul_f32 v[38:39], v[38:39], v[146:147] op_sel_hi:[1,0]
	v_pk_mul_f32 v[40:41], v[40:41], v[146:147] op_sel_hi:[1,0]
	v_cvt_pk_bf16_f32 v38, v38, v39
	v_cvt_pk_bf16_f32 v39, v40, v41
	global_store_short v156, v38, s[100:101] offset:32
	global_store_short_d16_hi v156, v38, s[100:101] offset:96
	global_store_short v156, v39, s[100:101] offset:160
	global_store_short_d16_hi v156, v39, s[100:101] offset:224
	v_pk_mul_f32 v[34:35], v[34:35], v[146:147] op_sel_hi:[1,0]
	v_pk_mul_f32 v[36:37], v[36:37], v[146:147] op_sel_hi:[1,0]
	v_cvt_pk_bf16_f32 v34, v34, v35
	v_cvt_pk_bf16_f32 v35, v36, v37
	global_store_short v156, v34, s[100:101] offset:1024
	global_store_short_d16_hi v156, v34, s[100:101] offset:1088
	global_store_short v156, v35, s[100:101] offset:1152
	global_store_short_d16_hi v156, v35, s[100:101] offset:1216
	s_add_u32 s100, s34, 0xa000
	s_addc_u32 s101, s35, 0
	v_pk_mul_f32 v[30:31], v[30:31], v[150:151] op_sel_hi:[1,0]
	v_pk_mul_f32 v[32:33], v[32:33], v[150:151] op_sel_hi:[1,0]
	v_cvt_pk_bf16_f32 v30, v30, v31
	v_cvt_pk_bf16_f32 v31, v32, v33
	global_store_short v156, v30, s[100:101]
	global_store_short_d16_hi v156, v30, s[100:101] offset:64
	global_store_short v156, v31, s[100:101] offset:128
	global_store_short_d16_hi v156, v31, s[100:101] offset:192
	v_pk_mul_f32 v[26:27], v[26:27], v[150:151] op_sel_hi:[1,0]
	v_pk_mul_f32 v[28:29], v[28:29], v[150:151] op_sel_hi:[1,0]
	v_cvt_pk_bf16_f32 v26, v26, v27
	v_cvt_pk_bf16_f32 v27, v28, v29
	global_store_short v156, v26, s[100:101] offset:1056
	global_store_short_d16_hi v156, v26, s[100:101] offset:1120
	global_store_short v156, v27, s[100:101] offset:1184
	global_store_short_d16_hi v156, v27, s[100:101] offset:1248
	s_add_u32 s100, s34, 0x10a000
	s_addc_u32 s101, s35, 0
	v_pk_mul_f32 v[22:23], v[22:23], v[150:151] op_sel_hi:[1,0]
	v_pk_mul_f32 v[24:25], v[24:25], v[150:151] op_sel_hi:[1,0]
	v_cvt_pk_bf16_f32 v22, v22, v23
	v_cvt_pk_bf16_f32 v23, v24, v25
	global_store_short v156, v22, s[100:101]
	global_store_short_d16_hi v156, v22, s[100:101] offset:64
	global_store_short v156, v23, s[100:101] offset:128
	global_store_short_d16_hi v156, v23, s[100:101] offset:192
	v_pk_mul_f32 v[18:19], v[18:19], v[150:151] op_sel_hi:[1,0]
	v_pk_mul_f32 v[20:21], v[20:21], v[150:151] op_sel_hi:[1,0]
	v_cvt_pk_bf16_f32 v18, v18, v19
	v_cvt_pk_bf16_f32 v19, v20, v21
	global_store_short v156, v18, s[100:101] offset:1056
	global_store_short_d16_hi v156, v18, s[100:101] offset:1120
	global_store_short v156, v19, s[100:101] offset:1184
	global_store_short_d16_hi v156, v19, s[100:101] offset:1248
	s_add_u32 s100, s34, 0xa000
	s_addc_u32 s101, s35, 0
	v_pk_mul_f32 v[14:15], v[14:15], v[154:155] op_sel_hi:[1,0]
	v_pk_mul_f32 v[16:17], v[16:17], v[154:155] op_sel_hi:[1,0]
	v_cvt_pk_bf16_f32 v14, v14, v15
	v_cvt_pk_bf16_f32 v15, v16, v17
	global_store_short v156, v14, s[100:101] offset:32
	global_store_short_d16_hi v156, v14, s[100:101] offset:96
	global_store_short v156, v15, s[100:101] offset:160
	global_store_short_d16_hi v156, v15, s[100:101] offset:224
	v_pk_mul_f32 v[10:11], v[10:11], v[154:155] op_sel_hi:[1,0]
	v_pk_mul_f32 v[12:13], v[12:13], v[154:155] op_sel_hi:[1,0]
	v_cvt_pk_bf16_f32 v10, v10, v11
	v_cvt_pk_bf16_f32 v11, v12, v13
	global_store_short v156, v10, s[100:101] offset:1024
	global_store_short_d16_hi v156, v10, s[100:101] offset:1088
	global_store_short v156, v11, s[100:101] offset:1152
	global_store_short_d16_hi v156, v11, s[100:101] offset:1216
	s_add_u32 s100, s34, 0x10a000
	s_addc_u32 s101, s35, 0
	v_pk_mul_f32 v[6:7], v[6:7], v[154:155] op_sel_hi:[1,0]
	v_pk_mul_f32 v[8:9], v[8:9], v[154:155] op_sel_hi:[1,0]
	v_cvt_pk_bf16_f32 v6, v6, v7
	v_cvt_pk_bf16_f32 v7, v8, v9
	global_store_short v156, v6, s[100:101] offset:32
	global_store_short_d16_hi v156, v6, s[100:101] offset:96
	global_store_short v156, v7, s[100:101] offset:160
	global_store_short_d16_hi v156, v7, s[100:101] offset:224
	v_pk_mul_f32 v[2:3], v[2:3], v[154:155] op_sel_hi:[1,0]
	v_pk_mul_f32 v[4:5], v[4:5], v[154:155] op_sel_hi:[1,0]
	v_cvt_pk_bf16_f32 v2, v2, v3
	v_cvt_pk_bf16_f32 v3, v4, v5
	global_store_short v156, v2, s[100:101] offset:1024
	global_store_short_d16_hi v156, v2, s[100:101] offset:1088
	global_store_short v156, v3, s[100:101] offset:1152
	global_store_short_d16_hi v156, v3, s[100:101] offset:1216
	s_branch .Lepo_done
; DI void st_bf16x4(bf16_t* p, f32x4 v) { u32x2 o; o.x = pk2e(v[0], v[1]); o.y = pk2e(v[2], v[3]); *(u32x2*)p = o; }
; DI void st_tr4(bf16_t* p, size_t stride, f32x4 v) { p[0] = f2bf(v[0]); p[stride] = f2bf(v[1]); p[2 * stride] = f2bf(v[2]); p[3 * stride] = f2bf(v[3]); }
;   DI float operator()(int row, int colbase, int fq, f32x4 v0, f32x4 v1) const { one(row, colbase + 4 * fq, v0); one(row, colbase + 16 + 4 * fq, v1); return 0.f; }
;   DI float operator()(int row, int colbase, int fq, f32x4 v0, f32x4 v1) const { one(row, colbase + 4 * fq, v0); one(row, colbase + 16 + 4 * fq, v1); return 0.f; }
;   DI float operator()(int row, int colbase, int fq, f32x4 v0, f32x4 v1) const { one(row, colbase + 4 * fq, v0); one(row, colbase + 16 + 4 * fq, v1); return 0.f; }
;   DI void one(int row, int c, f32x4 v) const {
;     const int b = row >> 12, t = row & 4095;
;     if (c < 2048) { const int h = c >> 7, d = c & 127; st_bf16x4((bf16_t*)(ws + O_NQ) + ((size_t)(b * 16 + h) * T_ + t) * 128 + d, v); }
;     else if (c < 5120) {
;       const int seg = (c - 2048) >> 9, cc = (c - 2048) & 511, g = cc >> 7, d = cc & 127;
;       if (seg == 3 || seg == 5) st_tr4((bf16_t*)(ws + (seg == 3 ? O_VST : O_VWT)) + (size_t)(b * 4 + g) * 128 * T_ + (size_t)(t >> 5) * 4096 + d * 32 + ((((t & 31) >> 2) ^ ((d >> 2) & 7)) << 2) + (t & 3), 32, v);
;       else { const size_t off = seg == 0 ? O_KC : seg == 1 ? O_VC : seg == 2 ? O_KS : O_KW;
;         st_bf16x4((bf16_t*)(ws + off) + ((size_t)(b * 4 + g) * T_ + t) * 128 + d, v); }
;     } else if (c < 5168) { *(f32x4*)((float*)(ws + O_GT) + (size_t)row * 48 + (c - 5120)) = v; }
;   }
;   DI float operator()(int row, int colbase, int fq, f32x4 v0, f32x4 v1) const { one(row, colbase + 4 * fq, v0); one(row, colbase + 16 + 4 * fq, v1); return 0.f; }
.Lepo_generic:
	s_nop 0
	v_readlane_b32 s0, v253, 48
	v_readlane_b32 s1, v253, 49
	v_or_b32_e32 v147, s8, v155
	s_ashr_i32 s30, s9, 12
	v_and_b32_e32 v146, 3, v148
	s_lshl_b32 s29, s30, 2
	v_bitop3_b32 v148, v152, 12, v148 bitop3:0x48
	s_waitcnt vmcnt(14)
	v_mov_b32_e32 v150, v162
	v_mov_b32_e32 v151, v166
	v_mov_b32_e32 v166, v163
	v_pk_add_f32 v[162:163], v[150:151], v[166:167]
	v_mov_b32_e32 v166, v164
	v_mov_b32_e32 v167, v168
	v_mov_b32_e32 v168, v165
	v_pk_add_f32 v[164:165], v[166:167], v[168:169]
	s_nop 0
	v_pk_add_f32 v[162:163], v[162:163], v[164:165]
	s_nop 0
	v_add_f32_e32 v0, v162, v163
	v_fmamk_f32 v0, v0, 0x3a000000, v249
	v_cmp_gt_f32_e32 vcc, s84, v0
	v_mul_f32_e32 v134, 0x4b800000, v0
	s_nop 0
	v_cndmask_b32_e32 v0, v0, v134, vcc
	v_rsq_f32_e32 v0, v0
	s_nop 0
	v_mul_f32_e32 v134, 0x45800000, v0
	v_cndmask_b32_e32 v138, v0, v134, vcc
	v_mov_b64_e32 v[134:135], s[0:1]
	v_mad_i64_i32 v[140:141], s[0:1], v142, s75, v[134:135]
	v_lshlrev_b32_e32 v134, 7, v142
	v_and_b32_e32 v0, 0x7e780, v134
	v_and_b32_e32 v156, 0x7e000, v134
	v_or_b32_e32 v134, s21, v147
	s_movk_i32 s0, 0x7ff
	v_pk_mul_f32 v[128:129], v[128:129], v[138:139] op_sel_hi:[1,0]
	v_pk_mul_f32 v[126:127], v[126:127], v[138:139] op_sel_hi:[1,0]
	v_cmp_lt_i32_e64 s[38:39], s0, v134
	s_and_saveexec_b64 s[0:1], s[38:39]
	s_xor_b64 s[10:11], exec, s[0:1]
	s_cbranch_execz .LBB0_467
	s_cmpk_gt_u32 s8, 0x13ff
	s_mov_b64 s[0:1], -1
	s_cbranch_scc0 .LBB0_457
	s_movk_i32 s0, 0x1430
	v_cmp_gt_u32_e32 vcc, s0, v134
	s_and_saveexec_b64 s[0:1], vcc
	s_cbranch_execz .LBB0_456
	v_mov_b32_e32 v135, v1
	v_lshl_add_u64 v[136:137], v[134:135], 2, v[140:141]
	v_add_co_u32_e32 v136, vcc, 0x2a160000, v136
	s_nop 1
	v_addc_co_u32_e32 v137, vcc, 0, v137, vcc
	global_store_dwordx4 v[136:137], v[126:129], off

;     ...
;   for (int u = (int)((blockIdx.x + gridDim.x - blk_off) % gridDim.x); u < nwg; u += gridDim.x) {
;     ...
;     __syncthreads();
;   }
.Lepe_done:
	v_readlane_b32 s8, v250, 1
	s_add_i32 s29, s29, s8
	s_cmpk_lt_i32 s29, 0x3a0
	s_barrier
	v_readlane_b32 s9, v250, 2
	s_cbranch_scc0 .LBB0_1807

; #define TIDX launder((int)threadIdx.x)
; DI void st_bf16x4(bf16_t* p, f32x4 v) { u32x2 o; o.x = pk2e(v[0], v[1]); o.y = pk2e(v[2], v[3]); *(u32x2*)p = o; }
;     ...
;     float rowss[2][4];
;     const int lane_e = TIDX & 63, fr_e = lane_e & 15, fq_e = lane_e >> 4;
; #pragma unroll
;     for (int ai = 0; ai < 2; ++ai)
; #pragma unroll
;       for (int m = 0; m < 4; ++m) {
;         const int row = brow + ai * HALF + wr * 64 + m * 16 + fr_e;
;         const float rsc = epi.rowscale(row);
;         float ssq = 0.f;
; #pragma unroll
;         for (int bj = 0; bj < 2; ++bj)
;           ssq += epi(row, bcol + bj * HALF + wc * 32, fq_e, acc[ai][bj][m][0] * rsc, acc[ai][bj][m][1] * rsc);
;         rowss[ai][m] = ssq;
;         __builtin_amdgcn_sched_barrier(0);
;       }
;   DI float rowscale(int row) const { const f32x4 a = *(const f32x4*)(ssp_in + (size_t)row * 8), b = *(const f32x4*)(ssp_in + (size_t)row * 8 + 4);
;     return rsqrtf((((a[0] + a[1]) + (a[2] + a[3])) + ((b[0] + b[1]) + (b[2] + b[3]))) * (1.f / D_) + EPS_); }
;   DI void one(int row, int c, f32x4 v) const {
;     const int b = row >> 12, t = row & 4095;
;     if (c < 3072) {
;       const int seg = c >> 10, cc = c & 1023, h = cc >> 7, d = cc & 127;
;       if (seg < 2) st_bf16x4((bf16_t*)(ws + (seg == 0 ? E_FQ : E_FK)) + ((size_t)(b * 8 + h) * T_ + t) * 128 + d, v);
;       else st_tr4((bf16_t*)(ws + E_FVT) + (size_t)(b * 8 + h) * 128 * T_ + (size_t)(t >> 5) * 4096 + d * 32 + ((((t & 31) >> 2) ^ ((d >> 2) & 7)) << 2) + (t & 3), 32, v);
;     } else if (c < 4096) { st_bf16x4((bf16_t*)(ws + E_HQ) + (size_t)row * 1024 + (c - 3072), v);
;     } else if (c < 5120) { *(f32x4*)((float*)(ws + E_HF) + (size_t)row * 1024 + (c - 4096)) = v;
;     } else if (c < 6144) { const int cc = c - 5120, h = cc >> 7, d = cc & 127; st_tr4((bf16_t*)(ws + E_HIT) + (size_t)(b * 8 + h) * 128 * T_ + (size_t)(t >> 5) * 4096 + d * 32 + (t & 31), 32, v);
;     } else if (c < 7168) { st_bf16x4((bf16_t*)(ws + E_HG) + (size_t)row * 1024 + (c - 6144), v);
;     } else if (c < 7176) { *(f32x4*)((float*)(ws + E_FF) + (size_t)row * 8 + (c - 7168)) = v; }
;   }
;   DI float operator()(int row, int colbase, int fq, f32x4 v0, f32x4 v1) const { one(row, colbase + 4 * fq, v0); one(row, colbase + 16 + 4 * fq, v1); return 0.f; }
.LBB0_1008:
	v_mov_b32_e32 v143, v199
	s_add_i32 s9, s10, s22
	v_and_b32_e32 v151, 15, v143
	s_ashr_i32 s10, s9, 9
	v_or_b32_e32 v146, s9, v151
	s_and_b32 s18, s10, -8
	v_ashrrev_i32_e32 v147, 31, v146
	v_readlane_b32 s10, v253, 52
	v_lshlrev_b64 v[144:145], 5, v[146:147]
	v_readlane_b32 s11, v253, 53
	v_lshrrev_b32_e32 v153, 2, v143
	v_and_b32_e32 v157, 12, v153
	v_lshl_add_u64 v[138:139], s[10:11], 0, v[144:145]
	s_mov_b64 s[100:101], 0x1000
	v_lshl_add_u64 v[240:241], v[138:139], 0, s[100:101]
	global_load_dwordx4 v[162:165], v[240:241], off offset:-4096
	global_load_dwordx4 v[166:169], v[240:241], off offset:-4080
	global_load_dwordx4 v[170:173], v[240:241], off offset:-3584
	global_load_dwordx4 v[174:177], v[240:241], off offset:-3568
	global_load_dwordx4 v[178:181], v[240:241], off offset:-3072
	global_load_dwordx4 v[182:185], v[240:241], off offset:-3056
	global_load_dwordx4 v[200:203], v[240:241], off offset:-2560
	global_load_dwordx4 v[204:207], v[240:241], off offset:-2544
	global_load_dwordx4 v[208:211], v[240:241], off
	global_load_dwordx4 v[212:215], v[240:241], off offset:16
	global_load_dwordx4 v[216:219], v[240:241], off offset:512
	global_load_dwordx4 v[220:223], v[240:241], off offset:528
	global_load_dwordx4 v[224:227], v[240:241], off offset:1024
	global_load_dwordx4 v[228:231], v[240:241], off offset:1040
	global_load_dwordx4 v[232:235], v[240:241], off offset:1536
	global_load_dwordx4 v[236:239], v[240:241], off offset:1552
	s_lshr_b32 s100, s8, 8
	s_cmp_lt_u32 s100, 28
	s_cbranch_scc0 .Lepe_generic
	s_mov_b32 s10, s100
	s_waitcnt vmcnt(14)
	v_add_f32_e32 v162, v162, v163
	v_add_f32_e32 v164, v164, v165
	v_add_f32_e32 v166, v166, v167
	v_add_f32_e32 v168, v168, v169
	v_add_f32_e32 v162, v162, v164
	v_add_f32_e32 v166, v166, v168
	v_add_f32_e32 v162, v162, v166
	v_fmamk_f32 v162, v162, 0x3a000000, v249
	v_cmp_gt_f32_e32 vcc, s84, v162
	v_mul_f32_e32 v163, 0x4b800000, v162
	s_nop 0
	v_cndmask_b32_e32 v162, v162, v163, vcc
	v_rsq_f32_e32 v162, v162
	s_nop 0
	v_mul_f32_e32 v163, 0x45800000, v162
	v_cndmask_b32_e32 v134, v162, v163, vcc
	s_waitcnt vmcnt(12)
	v_add_f32_e32 v170, v170, v171
	v_add_f32_e32 v172, v172, v173
	v_add_f32_e32 v174, v174, v175
	v_add_f32_e32 v176, v176, v177
	v_add_f32_e32 v170, v170, v172
	v_add_f32_e32 v174, v174, v176
	v_add_f32_e32 v170, v170, v174
	v_fmamk_f32 v170, v170, 0x3a000000, v249
	v_cmp_gt_f32_e32 vcc, s84, v170
	v_mul_f32_e32 v171, 0x4b800000, v170
	s_nop 0
	v_cndmask_b32_e32 v170, v170, v171, vcc
	v_rsq_f32_e32 v170, v170
	s_nop 0
	v_mul_f32_e32 v171, 0x45800000, v170
	v_cndmask_b32_e32 v136, v170, v171, vcc
	s_waitcnt vmcnt(10)
	v_add_f32_e32 v178, v178, v179
	v_add_f32_e32 v180, v180, v181
	v_add_f32_e32 v182, v182, v183
	v_add_f32_e32 v184, v184, v185
	v_add_f32_e32 v178, v178, v180
	v_add_f32_e32 v182, v182, v184
	v_add_f32_e32 v178, v178, v182
	v_fmamk_f32 v178, v178, 0x3a000000, v249
	v_cmp_gt_f32_e32 vcc, s84, v178
	v_mul_f32_e32 v179, 0x4b800000, v178
	s_nop 0
	v_cndmask_b32_e32 v178, v178, v179, vcc
	v_rsq_f32_e32 v178, v178
	s_nop 0
	v_mul_f32_e32 v179, 0x45800000, v178
	v_cndmask_b32_e32 v138, v178, v179, vcc
	s_waitcnt vmcnt(8)
	v_add_f32_e32 v200, v200, v201
	v_add_f32_e32 v202, v202, v203
	v_add_f32_e32 v204, v204, v205
	v_add_f32_e32 v206, v206, v207
	v_add_f32_e32 v200, v200, v202
	v_add_f32_e32 v204, v204, v206
	v_add_f32_e32 v200, v200, v204
	v_fmamk_f32 v200, v200, 0x3a000000, v249
	v_cmp_gt_f32_e32 vcc, s84, v200
	v_mul_f32_e32 v201, 0x4b800000, v200
	s_nop 0
	v_cndmask_b32_e32 v200, v200, v201, vcc
	v_rsq_f32_e32 v200, v200
	s_nop 0
	v_mul_f32_e32 v201, 0x45800000, v200
	v_cndmask_b32_e32 v140, v200, v201, vcc
	s_waitcnt vmcnt(6)
	v_add_f32_e32 v208, v208, v209
	v_add_f32_e32 v210, v210, v211
	v_add_f32_e32 v212, v212, v213
	v_add_f32_e32 v214, v214, v215
	v_add_f32_e32 v208, v208, v210
	v_add_f32_e32 v212, v212, v214
	v_add_f32_e32 v208, v208, v212
	v_fmamk_f32 v208, v208, 0x3a000000, v249
	v_cmp_gt_f32_e32 vcc, s84, v208
	v_mul_f32_e32 v209, 0x4b800000, v208
	s_nop 0
	v_cndmask_b32_e32 v208, v208, v209, vcc
	v_rsq_f32_e32 v208, v208
	s_nop 0
	v_mul_f32_e32 v209, 0x45800000, v208
	v_cndmask_b32_e32 v142, v208, v209, vcc
	s_waitcnt vmcnt(4)
	v_add_f32_e32 v216, v216, v217
	v_add_f32_e32 v218, v218, v219
	v_add_f32_e32 v220, v220, v221
	v_add_f32_e32 v222, v222, v223
	v_add_f32_e32 v216, v216, v218
	v_add_f32_e32 v220, v220, v222
	v_add_f32_e32 v216, v216, v220
	v_fmamk_f32 v216, v216, 0x3a000000, v249
	v_cmp_gt_f32_e32 vcc, s84, v216
	v_mul_f32_e32 v217, 0x4b800000, v216
	s_nop 0
	v_cndmask_b32_e32 v216, v216, v217, vcc
	v_rsq_f32_e32 v216, v216
	s_nop 0
	v_mul_f32_e32 v217, 0x45800000, v216
	v_cndmask_b32_e32 v146, v216, v217, vcc
	s_waitcnt vmcnt(2)
	v_add_f32_e32 v224, v224, v225
	v_add_f32_e32 v226, v226, v227
	v_add_f32_e32 v228, v228, v229
	v_add_f32_e32 v230, v230, v231
	v_add_f32_e32 v224, v224, v226
	v_add_f32_e32 v228, v228, v230
	v_add_f32_e32 v224, v224, v228
	v_fmamk_f32 v224, v224, 0x3a000000, v249
	v_cmp_gt_f32_e32 vcc, s84, v224
	v_mul_f32_e32 v225, 0x4b800000, v224
	s_nop 0
	v_cndmask_b32_e32 v224, v224, v225, vcc
	v_rsq_f32_e32 v224, v224
	s_nop 0
	v_mul_f32_e32 v225, 0x45800000, v224
	v_cndmask_b32_e32 v150, v224, v225, vcc
	s_waitcnt vmcnt(0)
	v_add_f32_e32 v232, v232, v233
	v_add_f32_e32 v234, v234, v235
	v_add_f32_e32 v236, v236, v237
	v_add_f32_e32 v238, v238, v239
	v_add_f32_e32 v232, v232, v234
	v_add_f32_e32 v236, v236, v238
	v_add_f32_e32 v232, v232, v236
	v_fmamk_f32 v232, v232, 0x3a000000, v249
	v_cmp_gt_f32_e32 vcc, s84, v232
	v_mul_f32_e32 v233, 0x4b800000, v232
	s_nop 0
	v_cndmask_b32_e32 v232, v232, v233, vcc
	v_rsq_f32_e32 v232, v232
	s_nop 0
	v_mul_f32_e32 v233, 0x45800000, v232
	v_cndmask_b32_e32 v154, v232, v233, vcc
	v_and_b32_e32 v157, 15, v199
	v_bfe_u32 v158, v199, 4, 2
	v_readlane_b32 s30, v253, 48
	v_readlane_b32 s31, v253, 49
	s_and_b32 s9, s9, 0xffffff00
	s_lshr_b32 s11, s9, 12
	s_and_b32 s12, s9, 0xfff
	s_lshl_b32 s12, s12, 8
	s_lshr_b32 s13, s10, 2
	s_and_b32 s14, s10, 3
	s_cmp_lt_u32 s13, 2
	s_cbranch_scc1 .Lepe_a
; DI unsigned pk2e(float lo, float hi) { const f32x2e f = {lo, hi}; const hwbf16x2e r = __builtin_convertvector(f, hwbf16x2e); return __builtin_bit_cast(unsigned, r); }
; DI void st_tr4(bf16_t* p, size_t stride, f32x4 v) { p[0] = f2bf(v[0]); p[stride] = f2bf(v[1]); p[2 * stride] = f2bf(v[2]); p[3 * stride] = f2bf(v[3]); }
;   DI float operator()(int row, int colbase, int fq, f32x4 v0, f32x4 v1) const { one(row, colbase + 4 * fq, v0); one(row, colbase + 16 + 4 * fq, v1); return 0.f; }
;   DI float operator()(int row, int colbase, int fq, f32x4 v0, f32x4 v1) const { one(row, colbase + 4 * fq, v0); one(row, colbase + 16 + 4 * fq, v1); return 0.f; }
;   DI float operator()(int row, int colbase, int fq, f32x4 v0, f32x4 v1) const { one(row, colbase + 4 * fq, v0); one(row, colbase + 16 + 4 * fq, v1); return 0.f; }
; DI void st_bf16x4(bf16_t* p, f32x4 v) { u32x2 o; o.x = pk2e(v[0], v[1]); o.y = pk2e(v[2], v[3]); *(u32x2*)p = o; }
;   DI void one(int row, int c, f32x4 v) const {
;     const int b = row >> 12, t = row & 4095;
;     if (c < 3072) {
;       const int seg = c >> 10, cc = c & 1023, h = cc >> 7, d = cc & 127;
;       if (seg < 2) st_bf16x4((bf16_t*)(ws + (seg == 0 ? E_FQ : E_FK)) + ((size_t)(b * 8 + h) * T_ + t) * 128 + d, v);
;       else st_tr4((bf16_t*)(ws + E_FVT) + (size_t)(b * 8 + h) * 128 * T_ + (size_t)(t >> 5) * 4096 + d * 32 + ((((t & 31) >> 2) ^ ((d >> 2) & 7)) << 2) + (t & 3), 32, v);
;     } else if (c < 4096) { st_bf16x4((bf16_t*)(ws + E_HQ) + (size_t)row * 1024 + (c - 3072), v);
;     } else if (c < 5120) { *(f32x4*)((float*)(ws + E_HF) + (size_t)row * 1024 + (c - 4096)) = v;
;     } else if (c < 6144) { const int cc = c - 5120, h = cc >> 7, d = cc & 127; st_tr4((bf16_t*)(ws + E_HIT) + (size_t)(b * 8 + h) * 128 * T_ + (size_t)(t >> 5) * 4096 + d * 32 + (t & 31), 32, v);
;     } else if (c < 7168) { st_bf16x4((bf16_t*)(ws + E_HG) + (size_t)row * 1024 + (c - 6144), v);
;     } else if (c < 7176) { *(f32x4*)((float*)(ws + E_FF) + (size_t)row * 8 + (c - 7168)) = v; }
;   }
;   DI float operator()(int row, int colbase, int fq, f32x4 v0, f32x4 v1) const { one(row, colbase + 4 * fq, v0); one(row, colbase + 16 + 4 * fq, v1); return 0.f; }
	s_cmp_eq_u32 s13, 2
	s_cbranch_scc1 .Lepe_dswz
	s_cmp_eq_u32 s13, 4
	s_cbranch_scc1 .Lepe_c
	s_cmp_eq_u32 s13, 5
	s_cbranch_scc1 .Lepe_dpl
	s_mov_b32 s15, 0x28145000
	s_cmp_eq_u32 s13, 6
	s_cmov_b32 s15, 0x2c145000
	s_lshl_b32 s16, s9, 11
	s_lshl_b32 s17, s14, 9
	s_add_i32 s16, s16, s17
	s_add_u32 s16, s16, s15
	s_add_u32 s34, s30, s16
	s_addc_u32 s35, s31, 0
	v_lshlrev_b32_e32 v156, 11, v157
	v_lshl_add_u32 v156, v158, 3, v156
	s_lshl_b32 s17, s22, 11
	s_lshl_b32 s16, s23, 1
	s_add_i32 s17, s17, s16
	v_add_u32_e32 v156, s17, v156
	s_mov_b64 s[100:101], s[34:35]
	v_pk_mul_f32 v[126:127], v[126:127], v[134:135] op_sel_hi:[1,0]
	v_pk_mul_f32 v[128:129], v[128:129], v[134:135] op_sel_hi:[1,0]
	v_cvt_pk_bf16_f32 v126, v126, v127
	v_cvt_pk_bf16_f32 v127, v128, v129
	global_store_dwordx2 v156, v[126:127], s[100:101]
	v_pk_mul_f32 v[122:123], v[122:123], v[134:135] op_sel_hi:[1,0]
	v_pk_mul_f32 v[124:125], v[124:125], v[134:135] op_sel_hi:[1,0]
	v_cvt_pk_bf16_f32 v122, v122, v123
	v_cvt_pk_bf16_f32 v123, v124, v125
	global_store_dwordx2 v156, v[122:123], s[100:101] offset:32
	v_pk_mul_f32 v[118:119], v[118:119], v[134:135] op_sel_hi:[1,0]
	v_pk_mul_f32 v[120:121], v[120:121], v[134:135] op_sel_hi:[1,0]
	v_cvt_pk_bf16_f32 v118, v118, v119
	v_cvt_pk_bf16_f32 v119, v120, v121
	global_store_dwordx2 v156, v[118:119], s[100:101] offset:256
	v_pk_mul_f32 v[114:115], v[114:115], v[134:135] op_sel_hi:[1,0]
	v_pk_mul_f32 v[116:117], v[116:117], v[134:135] op_sel_hi:[1,0]
	v_cvt_pk_bf16_f32 v114, v114, v115
	v_cvt_pk_bf16_f32 v115, v116, v117
	global_store_dwordx2 v156, v[114:115], s[100:101] offset:288
	s_add_u32 s100, s34, 0x8000
	s_addc_u32 s101, s35, 0
	v_pk_mul_f32 v[110:111], v[110:111], v[136:137] op_sel_hi:[1,0]
	v_pk_mul_f32 v[112:113], v[112:113], v[136:137] op_sel_hi:[1,0]
	v_cvt_pk_bf16_f32 v110, v110, v111
	v_cvt_pk_bf16_f32 v111, v112, v113
	global_store_dwordx2 v156, v[110:111], s[100:101]
	v_pk_mul_f32 v[106:107], v[106:107], v[136:137] op_sel_hi:[1,0]
	v_pk_mul_f32 v[108:109], v[108:109], v[136:137] op_sel_hi:[1,0]
	v_cvt_pk_bf16_f32 v106, v106, v107
	v_cvt_pk_bf16_f32 v107, v108, v109
	global_store_dwordx2 v156, v[106:107], s[100:101] offset:32
	v_pk_mul_f32 v[102:103], v[102:103], v[136:137] op_sel_hi:[1,0]
	v_pk_mul_f32 v[104:105], v[104:105], v[136:137] op_sel_hi:[1,0]
	v_cvt_pk_bf16_f32 v102, v102, v103
	v_cvt_pk_bf16_f32 v103, v104, v105
	global_store_dwordx2 v156, v[102:103], s[100:101] offset:256
	v_pk_mul_f32 v[98:99], v[98:99], v[136:137] op_sel_hi:[1,0]
	v_pk_mul_f32 v[100:101], v[100:101], v[136:137] op_sel_hi:[1,0]
	v_cvt_pk_bf16_f32 v98, v98, v99
	v_cvt_pk_bf16_f32 v99, v100, v101
	global_store_dwordx2 v156, v[98:99], s[100:101] offset:288
	s_add_u32 s100, s34, 0x10000
	s_addc_u32 s101, s35, 0
	v_pk_mul_f32 v[94:95], v[94:95], v[138:139] op_sel_hi:[1,0]
	v_pk_mul_f32 v[96:97], v[96:97], v[138:139] op_sel_hi:[1,0]
	v_cvt_pk_bf16_f32 v94, v94, v95
	v_cvt_pk_bf16_f32 v95, v96, v97
	global_store_dwordx2 v156, v[94:95], s[100:101]
	v_pk_mul_f32 v[90:91], v[90:91], v[138:139] op_sel_hi:[1,0]
	v_pk_mul_f32 v[92:93], v[92:93], v[138:139] op_sel_hi:[1,0]
	v_cvt_pk_bf16_f32 v90, v90, v91
	v_cvt_pk_bf16_f32 v91, v92, v93
	global_store_dwordx2 v156, v[90:91], s[100:101] offset:32
	v_pk_mul_f32 v[86:87], v[86:87], v[138:139] op_sel_hi:[1,0]
	v_pk_mul_f32 v[88:89], v[88:89], v[138:139] op_sel_hi:[1,0]
	v_cvt_pk_bf16_f32 v86, v86, v87
	v_cvt_pk_bf16_f32 v87, v88, v89
	global_store_dwordx2 v156, v[86:87], s[100:101] offset:256
	v_pk_mul_f32 v[82:83], v[82:83], v[138:139] op_sel_hi:[1,0]
	v_pk_mul_f32 v[84:85], v[84:85], v[138:139] op_sel_hi:[1,0]
	v_cvt_pk_bf16_f32 v82, v82, v83
	v_cvt_pk_bf16_f32 v83, v84, v85
	global_store_dwordx2 v156, v[82:83], s[100:101] offset:288
	s_add_u32 s100, s34, 0x18000
	s_addc_u32 s101, s35, 0
	v_pk_mul_f32 v[78:79], v[78:79], v[140:141] op_sel_hi:[1,0]
	v_pk_mul_f32 v[80:81], v[80:81], v[140:141] op_sel_hi:[1,0]
	v_cvt_pk_bf16_f32 v78, v78, v79
	v_cvt_pk_bf16_f32 v79, v80, v81
	global_store_dwordx2 v156, v[78:79], s[100:101]
	v_pk_mul_f32 v[74:75], v[74:75], v[140:141] op_sel_hi:[1,0]
	v_pk_mul_f32 v[76:77], v[76:77], v[140:141] op_sel_hi:[1,0]
	v_cvt_pk_bf16_f32 v74, v74, v75
	v_cvt_pk_bf16_f32 v75, v76, v77
	global_store_dwordx2 v156, v[74:75], s[100:101] offset:32
	v_pk_mul_f32 v[70:71], v[70:71], v[140:141] op_sel_hi:[1,0]
	v_pk_mul_f32 v[72:73], v[72:73], v[140:141] op_sel_hi:[1,0]
	v_cvt_pk_bf16_f32 v70, v70, v71
	v_cvt_pk_bf16_f32 v71, v72, v73
	global_store_dwordx2 v156, v[70:71], s[100:101] offset:256
	v_pk_mul_f32 v[66:67], v[66:67], v[140:141] op_sel_hi:[1,0]
	v_pk_mul_f32 v[68:69], v[68:69], v[140:141] op_sel_hi:[1,0]
	v_cvt_pk_bf16_f32 v66, v66, v67
	v_cvt_pk_bf16_f32 v67, v68, v69
	global_store_dwordx2 v156, v[66:67], s[100:101] offset:288
	s_add_u32 s100, s34, 0x40000
	s_addc_u32 s101, s35, 0
	v_pk_mul_f32 v[62:63], v[62:63], v[142:143] op_sel_hi:[1,0]
	v_pk_mul_f32 v[64:65], v[64:65], v[142:143] op_sel_hi:[1,0]
	v_cvt_pk_bf16_f32 v62, v62, v63
	v_cvt_pk_bf16_f32 v63, v64, v65
	global_store_dwordx2 v156, v[62:63], s[100:101]
	v_pk_mul_f32 v[58:59], v[58:59], v[142:143] op_sel_hi:[1,0]
	v_pk_mul_f32 v[60:61], v[60:61], v[142:143] op_sel_hi:[1,0]
	v_cvt_pk_bf16_f32 v58, v58, v59
	v_cvt_pk_bf16_f32 v59, v60, v61
	global_store_dwordx2 v156, v[58:59], s[100:101] offset:32
	v_pk_mul_f32 v[54:55], v[54:55], v[142:143] op_sel_hi:[1,0]
	v_pk_mul_f32 v[56:57], v[56:57], v[142:143] op_sel_hi:[1,0]
	v_cvt_pk_bf16_f32 v54, v54, v55
	v_cvt_pk_bf16_f32 v55, v56, v57
	global_store_dwordx2 v156, v[54:55], s[100:101] offset:256
	v_pk_mul_f32 v[50:51], v[50:51], v[142:143] op_sel_hi:[1,0]
; DI unsigned pk2e(float lo, float hi) { const f32x2e f = {lo, hi}; const hwbf16x2e r = __builtin_convertvector(f, hwbf16x2e); return __builtin_bit_cast(unsigned, r); }
; DI void st_bf16x4(bf16_t* p, f32x4 v) { u32x2 o; o.x = pk2e(v[0], v[1]); o.y = pk2e(v[2], v[3]); *(u32x2*)p = o; }
;   DI void one(int row, int c, f32x4 v) const {
;     ...
;     if (c < 3072) {
;       const int seg = c >> 10, cc = c & 1023, h = cc >> 7, d = cc & 127;
;       if (seg < 2) st_bf16x4((bf16_t*)(ws + (seg == 0 ? E_FQ : E_FK)) + ((size_t)(b * 8 + h) * T_ + t) * 128 + d, v);
	v_pk_mul_f32 v[52:53], v[52:53], v[142:143] op_sel_hi:[1,0]
	v_cvt_pk_bf16_f32 v50, v50, v51
	v_cvt_pk_bf16_f32 v51, v52, v53
	global_store_dwordx2 v156, v[50:51], s[100:101] offset:288
	s_add_u32 s100, s34, 0x48000
	s_addc_u32 s101, s35, 0
	v_pk_mul_f32 v[46:47], v[46:47], v[146:147] op_sel_hi:[1,0]
	v_pk_mul_f32 v[48:49], v[48:49], v[146:147] op_sel_hi:[1,0]
	v_cvt_pk_bf16_f32 v46, v46, v47
	v_cvt_pk_bf16_f32 v47, v48, v49
	global_store_dwordx2 v156, v[46:47], s[100:101]
	v_pk_mul_f32 v[42:43], v[42:43], v[146:147] op_sel_hi:[1,0]
	v_pk_mul_f32 v[44:45], v[44:45], v[146:147] op_sel_hi:[1,0]
	v_cvt_pk_bf16_f32 v42, v42, v43
	v_cvt_pk_bf16_f32 v43, v44, v45
	global_store_dwordx2 v156, v[42:43], s[100:101] offset:32
	v_pk_mul_f32 v[38:39], v[38:39], v[146:147] op_sel_hi:[1,0]
	v_pk_mul_f32 v[40:41], v[40:41], v[146:147] op_sel_hi:[1,0]
	v_cvt_pk_bf16_f32 v38, v38, v39
	v_cvt_pk_bf16_f32 v39, v40, v41
	global_store_dwordx2 v156, v[38:39], s[100:101] offset:256
	v_pk_mul_f32 v[34:35], v[34:35], v[146:147] op_sel_hi:[1,0]
	v_pk_mul_f32 v[36:37], v[36:37], v[146:147] op_sel_hi:[1,0]
	v_cvt_pk_bf16_f32 v34, v34, v35
	v_cvt_pk_bf16_f32 v35, v36, v37
	global_store_dwordx2 v156, v[34:35], s[100:101] offset:288
	s_add_u32 s100, s34, 0x50000
	s_addc_u32 s101, s35, 0
	v_pk_mul_f32 v[30:31], v[30:31], v[150:151] op_sel_hi:[1,0]
	v_pk_mul_f32 v[32:33], v[32:33], v[150:151] op_sel_hi:[1,0]
	v_cvt_pk_bf16_f32 v30, v30, v31
	v_cvt_pk_bf16_f32 v31, v32, v33
	global_store_dwordx2 v156, v[30:31], s[100:101]
	v_pk_mul_f32 v[26:27], v[26:27], v[150:151] op_sel_hi:[1,0]
	v_pk_mul_f32 v[28:29], v[28:29], v[150:151] op_sel_hi:[1,0]
	v_cvt_pk_bf16_f32 v26, v26, v27
	v_cvt_pk_bf16_f32 v27, v28, v29
	global_store_dwordx2 v156, v[26:27], s[100:101] offset:32
	v_pk_mul_f32 v[22:23], v[22:23], v[150:151] op_sel_hi:[1,0]
	v_pk_mul_f32 v[24:25], v[24:25], v[150:151] op_sel_hi:[1,0]
	v_cvt_pk_bf16_f32 v22, v22, v23
	v_cvt_pk_bf16_f32 v23, v24, v25
	global_store_dwordx2 v156, v[22:23], s[100:101] offset:256
	v_pk_mul_f32 v[18:19], v[18:19], v[150:151] op_sel_hi:[1,0]
	v_pk_mul_f32 v[20:21], v[20:21], v[150:151] op_sel_hi:[1,0]
	v_cvt_pk_bf16_f32 v18, v18, v19
	v_cvt_pk_bf16_f32 v19, v20, v21
	global_store_dwordx2 v156, v[18:19], s[100:101] offset:288
	s_add_u32 s100, s34, 0x58000
	s_addc_u32 s101, s35, 0
	v_pk_mul_f32 v[14:15], v[14:15], v[154:155] op_sel_hi:[1,0]
	v_pk_mul_f32 v[16:17], v[16:17], v[154:155] op_sel_hi:[1,0]
	v_cvt_pk_bf16_f32 v14, v14, v15
	v_cvt_pk_bf16_f32 v15, v16, v17
	global_store_dwordx2 v156, v[14:15], s[100:101]
	v_pk_mul_f32 v[10:11], v[10:11], v[154:155] op_sel_hi:[1,0]
	v_pk_mul_f32 v[12:13], v[12:13], v[154:155] op_sel_hi:[1,0]
	v_cvt_pk_bf16_f32 v10, v10, v11
	v_cvt_pk_bf16_f32 v11, v12, v13
	global_store_dwordx2 v156, v[10:11], s[100:101] offset:32
	v_pk_mul_f32 v[6:7], v[6:7], v[154:155] op_sel_hi:[1,0]
	v_pk_mul_f32 v[8:9], v[8:9], v[154:155] op_sel_hi:[1,0]
	v_cvt_pk_bf16_f32 v6, v6, v7
	v_cvt_pk_bf16_f32 v7, v8, v9
	global_store_dwordx2 v156, v[6:7], s[100:101] offset:256
	v_pk_mul_f32 v[2:3], v[2:3], v[154:155] op_sel_hi:[1,0]
	v_pk_mul_f32 v[4:5], v[4:5], v[154:155] op_sel_hi:[1,0]
	v_cvt_pk_bf16_f32 v2, v2, v3
	v_cvt_pk_bf16_f32 v3, v4, v5
	global_store_dwordx2 v156, v[2:3], s[100:101] offset:288
	s_branch .Lepe_done
.Lepe_a:
	s_mov_b32 s15, 0x25145000
	s_cmp_eq_u32 s13, 1
	s_cmov_b32 s15, 0x26145000
	s_lshl_b32 s16, s11, 3
	s_lshl_b32 s17, s14, 1
	s_add_i32 s16, s16, s17
	s_lshl_b32 s16, s16, 20
	s_add_i32 s16, s16, s12
	s_add_u32 s16, s16, s15
	s_add_u32 s34, s30, s16
	s_addc_u32 s35, s31, 0
	v_lshlrev_b32_e32 v156, 8, v157
	v_lshl_add_u32 v156, v158, 3, v156
	s_lshl_b32 s17, s22, 8
	s_lshl_b32 s16, s23, 1
	s_add_i32 s17, s17, s16
	v_add_u32_e32 v156, s17, v156
	s_mov_b64 s[100:101], s[34:35]
	v_pk_mul_f32 v[126:127], v[126:127], v[134:135] op_sel_hi:[1,0]
	v_pk_mul_f32 v[128:129], v[128:129], v[134:135] op_sel_hi:[1,0]
	v_cvt_pk_bf16_f32 v126, v126, v127
	v_cvt_pk_bf16_f32 v127, v128, v129
	global_store_dwordx2 v156, v[126:127], s[100:101]
	v_pk_mul_f32 v[122:123], v[122:123], v[134:135] op_sel_hi:[1,0]
	v_pk_mul_f32 v[124:125], v[124:125], v[134:135] op_sel_hi:[1,0]
	v_cvt_pk_bf16_f32 v122, v122, v123
	v_cvt_pk_bf16_f32 v123, v124, v125
	global_store_dwordx2 v156, v[122:123], s[100:101] offset:32
	s_add_u32 s100, s34, 0x100000
	s_addc_u32 s101, s35, 0
	v_pk_mul_f32 v[118:119], v[118:119], v[134:135] op_sel_hi:[1,0]
	v_pk_mul_f32 v[120:121], v[120:121], v[134:135] op_sel_hi:[1,0]
	v_cvt_pk_bf16_f32 v118, v118, v119
	v_cvt_pk_bf16_f32 v119, v120, v121
	global_store_dwordx2 v156, v[118:119], s[100:101]
	v_pk_mul_f32 v[114:115], v[114:115], v[134:135] op_sel_hi:[1,0]
	v_pk_mul_f32 v[116:117], v[116:117], v[134:135] op_sel_hi:[1,0]
	v_cvt_pk_bf16_f32 v114, v114, v115
	v_cvt_pk_bf16_f32 v115, v116, v117
	global_store_dwordx2 v156, v[114:115], s[100:101] offset:32
	s_add_u32 s100, s34, 0x1000
	s_addc_u32 s101, s35, 0
	v_pk_mul_f32 v[110:111], v[110:111], v[136:137] op_sel_hi:[1,0]
	v_pk_mul_f32 v[112:113], v[112:113], v[136:137] op_sel_hi:[1,0]
	v_cvt_pk_bf16_f32 v110, v110, v111
	v_cvt_pk_bf16_f32 v111, v112, v113
	global_store_dwordx2 v156, v[110:111], s[100:101]
	v_pk_mul_f32 v[106:107], v[106:107], v[136:137] op_sel_hi:[1,0]
	v_pk_mul_f32 v[108:109], v[108:109], v[136:137] op_sel_hi:[1,0]
	v_cvt_pk_bf16_f32 v106, v106, v107
	v_cvt_pk_bf16_f32 v107, v108, v109
	global_store_dwordx2 v156, v[106:107], s[100:101] offset:32
	s_add_u32 s100, s34, 0x101000
	s_addc_u32 s101, s35, 0
	v_pk_mul_f32 v[102:103], v[102:103], v[136:137] op_sel_hi:[1,0]
	v_pk_mul_f32 v[104:105], v[104:105], v[136:137] op_sel_hi:[1,0]
	v_cvt_pk_bf16_f32 v102, v102, v103
; DI unsigned pk2e(float lo, float hi) { const f32x2e f = {lo, hi}; const hwbf16x2e r = __builtin_convertvector(f, hwbf16x2e); return __builtin_bit_cast(unsigned, r); }
; DI void st_bf16x4(bf16_t* p, f32x4 v) { u32x2 o; o.x = pk2e(v[0], v[1]); o.y = pk2e(v[2], v[3]); *(u32x2*)p = o; }
;   DI void one(int row, int c, f32x4 v) const {
;     ...
;     if (c < 3072) {
;       const int seg = c >> 10, cc = c & 1023, h = cc >> 7, d = cc & 127;
;       if (seg < 2) st_bf16x4((bf16_t*)(ws + (seg == 0 ? E_FQ : E_FK)) + ((size_t)(b * 8 + h) * T_ + t) * 128 + d, v);
	v_cvt_pk_bf16_f32 v103, v104, v105
	global_store_dwordx2 v156, v[102:103], s[100:101]
	v_pk_mul_f32 v[98:99], v[98:99], v[136:137] op_sel_hi:[1,0]
	v_pk_mul_f32 v[100:101], v[100:101], v[136:137] op_sel_hi:[1,0]
	v_cvt_pk_bf16_f32 v98, v98, v99
	v_cvt_pk_bf16_f32 v99, v100, v101
	global_store_dwordx2 v156, v[98:99], s[100:101] offset:32
	s_add_u32 s100, s34, 0x2000
	s_addc_u32 s101, s35, 0
	v_pk_mul_f32 v[94:95], v[94:95], v[138:139] op_sel_hi:[1,0]
	v_pk_mul_f32 v[96:97], v[96:97], v[138:139] op_sel_hi:[1,0]
	v_cvt_pk_bf16_f32 v94, v94, v95
	v_cvt_pk_bf16_f32 v95, v96, v97
	global_store_dwordx2 v156, v[94:95], s[100:101]
	v_pk_mul_f32 v[90:91], v[90:91], v[138:139] op_sel_hi:[1,0]
	v_pk_mul_f32 v[92:93], v[92:93], v[138:139] op_sel_hi:[1,0]
	v_cvt_pk_bf16_f32 v90, v90, v91
	v_cvt_pk_bf16_f32 v91, v92, v93
	global_store_dwordx2 v156, v[90:91], s[100:101] offset:32
	s_add_u32 s100, s34, 0x102000
	s_addc_u32 s101, s35, 0
	v_pk_mul_f32 v[86:87], v[86:87], v[138:139] op_sel_hi:[1,0]
	v_pk_mul_f32 v[88:89], v[88:89], v[138:139] op_sel_hi:[1,0]
	v_cvt_pk_bf16_f32 v86, v86, v87
	v_cvt_pk_bf16_f32 v87, v88, v89
	global_store_dwordx2 v156, v[86:87], s[100:101]
	v_pk_mul_f32 v[82:83], v[82:83], v[138:139] op_sel_hi:[1,0]
	v_pk_mul_f32 v[84:85], v[84:85], v[138:139] op_sel_hi:[1,0]
	v_cvt_pk_bf16_f32 v82, v82, v83
	v_cvt_pk_bf16_f32 v83, v84, v85
	global_store_dwordx2 v156, v[82:83], s[100:101] offset:32
	s_add_u32 s100, s34, 0x3000
	s_addc_u32 s101, s35, 0
	v_pk_mul_f32 v[78:79], v[78:79], v[140:141] op_sel_hi:[1,0]
	v_pk_mul_f32 v[80:81], v[80:81], v[140:141] op_sel_hi:[1,0]
	v_cvt_pk_bf16_f32 v78, v78, v79
	v_cvt_pk_bf16_f32 v79, v80, v81
	global_store_dwordx2 v156, v[78:79], s[100:101]
	v_pk_mul_f32 v[74:75], v[74:75], v[140:141] op_sel_hi:[1,0]
	v_pk_mul_f32 v[76:77], v[76:77], v[140:141] op_sel_hi:[1,0]
	v_cvt_pk_bf16_f32 v74, v74, v75
	v_cvt_pk_bf16_f32 v75, v76, v77
	global_store_dwordx2 v156, v[74:75], s[100:101] offset:32
	s_add_u32 s100, s34, 0x103000
	s_addc_u32 s101, s35, 0
	v_pk_mul_f32 v[70:71], v[70:71], v[140:141] op_sel_hi:[1,0]
	v_pk_mul_f32 v[72:73], v[72:73], v[140:141] op_sel_hi:[1,0]
	v_cvt_pk_bf16_f32 v70, v70, v71
	v_cvt_pk_bf16_f32 v71, v72, v73
	global_store_dwordx2 v156, v[70:71], s[100:101]
	v_pk_mul_f32 v[66:67], v[66:67], v[140:141] op_sel_hi:[1,0]
	v_pk_mul_f32 v[68:69], v[68:69], v[140:141] op_sel_hi:[1,0]
	v_cvt_pk_bf16_f32 v66, v66, v67
	v_cvt_pk_bf16_f32 v67, v68, v69
	global_store_dwordx2 v156, v[66:67], s[100:101] offset:32
	s_add_u32 s100, s34, 0x8000
	s_addc_u32 s101, s35, 0
	v_pk_mul_f32 v[62:63], v[62:63], v[142:143] op_sel_hi:[1,0]
	v_pk_mul_f32 v[64:65], v[64:65], v[142:143] op_sel_hi:[1,0]
	v_cvt_pk_bf16_f32 v62, v62, v63
	v_cvt_pk_bf16_f32 v63, v64, v65
	global_store_dwordx2 v156, v[62:63], s[100:101]
	v_pk_mul_f32 v[58:59], v[58:59], v[142:143] op_sel_hi:[1,0]
	v_pk_mul_f32 v[60:61], v[60:61], v[142:143] op_sel_hi:[1,0]
	v_cvt_pk_bf16_f32 v58, v58, v59
	v_cvt_pk_bf16_f32 v59, v60, v61
	global_store_dwordx2 v156, v[58:59], s[100:101] offset:32
	s_add_u32 s100, s34, 0x108000
	s_addc_u32 s101, s35, 0
	v_pk_mul_f32 v[54:55], v[54:55], v[142:143] op_sel_hi:[1,0]
	v_pk_mul_f32 v[56:57], v[56:57], v[142:143] op_sel_hi:[1,0]
	v_cvt_pk_bf16_f32 v54, v54, v55
	v_cvt_pk_bf16_f32 v55, v56, v57
	global_store_dwordx2 v156, v[54:55], s[100:101]
	v_pk_mul_f32 v[50:51], v[50:51], v[142:143] op_sel_hi:[1,0]
	v_pk_mul_f32 v[52:53], v[52:53], v[142:143] op_sel_hi:[1,0]
	v_cvt_pk_bf16_f32 v50, v50, v51
	v_cvt_pk_bf16_f32 v51, v52, v53
	global_store_dwordx2 v156, v[50:51], s[100:101] offset:32
	s_add_u32 s100, s34, 0x9000
	s_addc_u32 s101, s35, 0
	v_pk_mul_f32 v[46:47], v[46:47], v[146:147] op_sel_hi:[1,0]
	v_pk_mul_f32 v[48:49], v[48:49], v[146:147] op_sel_hi:[1,0]
	v_cvt_pk_bf16_f32 v46, v46, v47
	v_cvt_pk_bf16_f32 v47, v48, v49
	global_store_dwordx2 v156, v[46:47], s[100:101]
	v_pk_mul_f32 v[42:43], v[42:43], v[146:147] op_sel_hi:[1,0]
	v_pk_mul_f32 v[44:45], v[44:45], v[146:147] op_sel_hi:[1,0]
	v_cvt_pk_bf16_f32 v42, v42, v43
	v_cvt_pk_bf16_f32 v43, v44, v45
	global_store_dwordx2 v156, v[42:43], s[100:101] offset:32
	s_add_u32 s100, s34, 0x109000
	s_addc_u32 s101, s35, 0
	v_pk_mul_f32 v[38:39], v[38:39], v[146:147] op_sel_hi:[1,0]
	v_pk_mul_f32 v[40:41], v[40:41], v[146:147] op_sel_hi:[1,0]
	v_cvt_pk_bf16_f32 v38, v38, v39
	v_cvt_pk_bf16_f32 v39, v40, v41
	global_store_dwordx2 v156, v[38:39], s[100:101]
	v_pk_mul_f32 v[34:35], v[34:35], v[146:147] op_sel_hi:[1,0]
	v_pk_mul_f32 v[36:37], v[36:37], v[146:147] op_sel_hi:[1,0]
	v_cvt_pk_bf16_f32 v34, v34, v35
	v_cvt_pk_bf16_f32 v35, v36, v37
	global_store_dwordx2 v156, v[34:35], s[100:101] offset:32
	s_add_u32 s100, s34, 0xa000
	s_addc_u32 s101, s35, 0
	v_pk_mul_f32 v[30:31], v[30:31], v[150:151] op_sel_hi:[1,0]
	v_pk_mul_f32 v[32:33], v[32:33], v[150:151] op_sel_hi:[1,0]
	v_cvt_pk_bf16_f32 v30, v30, v31
	v_cvt_pk_bf16_f32 v31, v32, v33
	global_store_dwordx2 v156, v[30:31], s[100:101]
	v_pk_mul_f32 v[26:27], v[26:27], v[150:151] op_sel_hi:[1,0]
	v_pk_mul_f32 v[28:29], v[28:29], v[150:151] op_sel_hi:[1,0]
	v_cvt_pk_bf16_f32 v26, v26, v27
	v_cvt_pk_bf16_f32 v27, v28, v29
	global_store_dwordx2 v156, v[26:27], s[100:101] offset:32
	s_add_u32 s100, s34, 0x10a000
	s_addc_u32 s101, s35, 0
	v_pk_mul_f32 v[22:23], v[22:23], v[150:151] op_sel_hi:[1,0]
	v_pk_mul_f32 v[24:25], v[24:25], v[150:151] op_sel_hi:[1,0]
	v_cvt_pk_bf16_f32 v22, v22, v23
	v_cvt_pk_bf16_f32 v23, v24, v25
	global_store_dwordx2 v156, v[22:23], s[100:101]
	v_pk_mul_f32 v[18:19], v[18:19], v[150:151] op_sel_hi:[1,0]
	v_pk_mul_f32 v[20:21], v[20:21], v[150:151] op_sel_hi:[1,0]
	v_cvt_pk_bf16_f32 v18, v18, v19
	v_cvt_pk_bf16_f32 v19, v20, v21
	global_store_dwordx2 v156, v[18:19], s[100:101] offset:32
	s_add_u32 s100, s34, 0xb000
	s_addc_u32 s101, s35, 0
	v_pk_mul_f32 v[14:15], v[14:15], v[154:155] op_sel_hi:[1,0]
	v_pk_mul_f32 v[16:17], v[16:17], v[154:155] op_sel_hi:[1,0]
	v_cvt_pk_bf16_f32 v14, v14, v15
	v_cvt_pk_bf16_f32 v15, v16, v17
	global_store_dwordx2 v156, v[14:15], s[100:101]
	v_pk_mul_f32 v[10:11], v[10:11], v[154:155] op_sel_hi:[1,0]
	v_pk_mul_f32 v[12:13], v[12:13], v[154:155] op_sel_hi:[1,0]
	v_cvt_pk_bf16_f32 v10, v10, v11
	v_cvt_pk_bf16_f32 v11, v12, v13
	global_store_dwordx2 v156, v[10:11], s[100:101] offset:32
	s_add_u32 s100, s34, 0x10b000
	s_addc_u32 s101, s35, 0
	v_pk_mul_f32 v[6:7], v[6:7], v[154:155] op_sel_hi:[1,0]
	v_pk_mul_f32 v[8:9], v[8:9], v[154:155] op_sel_hi:[1,0]
	v_cvt_pk_bf16_f32 v6, v6, v7
	v_cvt_pk_bf16_f32 v7, v8, v9
	global_store_dwordx2 v156, v[6:7], s[100:101]
	v_pk_mul_f32 v[2:3], v[2:3], v[154:155] op_sel_hi:[1,0]
	v_pk_mul_f32 v[4:5], v[4:5], v[154:155] op_sel_hi:[1,0]
	v_cvt_pk_bf16_f32 v2, v2, v3
	v_cvt_pk_bf16_f32 v3, v4, v5
	global_store_dwordx2 v156, v[2:3], s[100:101] offset:32
	s_branch .Lepe_done
; DI bf16_t f2bf(float x) { return (bf16_t)(pk2(x, 0.f) & 0xffffu); }
; DI void st_tr4(bf16_t* p, size_t stride, f32x4 v) { p[0] = f2bf(v[0]); p[stride] = f2bf(v[1]); p[2 * stride] = f2bf(v[2]); p[3 * stride] = f2bf(v[3]); }
;   DI void one(int row, int c, f32x4 v) const {
;     ...
;       else st_tr4((bf16_t*)(ws + E_FVT) + (size_t)(b * 8 + h) * 128 * T_ + (size_t)(t >> 5) * 4096 + d * 32 + ((((t & 31) >> 2) ^ ((d >> 2) & 7)) << 2) + (t & 3), 32, v);
.Lepe_dswz:
	s_lshl_b32 s16, s11, 3
	s_lshl_b32 s17, s14, 1
	s_add_i32 s16, s16, s17
	s_lshl_b32 s16, s16, 20
	s_add_i32 s16, s16, s12
	s_add_u32 s16, s16, 0x27145000
	s_add_u32 s34, s30, s16
	s_addc_u32 s35, s31, 0
	v_lshrrev_b32_e32 v159, 2, v157
	v_xor_b32_e32 v159, v159, v158
	v_and_b32_e32 v156, 3, v157
	v_lshl_add_u32 v156, v159, 2, v156
	v_lshlrev_b32_e32 v156, 1, v156
	v_lshl_add_u32 v156, v158, 8, v156
	s_lshl_b32 s17, s22, 8
	s_lshl_b32 s16, s23, 6
	s_add_i32 s17, s17, s16
	v_add_u32_e32 v156, s17, v156
	s_mov_b64 s[100:101], s[34:35]
	v_pk_mul_f32 v[126:127], v[126:127], v[134:135] op_sel_hi:[1,0]
	v_pk_mul_f32 v[128:129], v[128:129], v[134:135] op_sel_hi:[1,0]
	v_cvt_pk_bf16_f32 v126, v126, v127
	v_cvt_pk_bf16_f32 v127, v128, v129
	global_store_short v156, v126, s[100:101]
	global_store_short_d16_hi v156, v126, s[100:101] offset:64
	global_store_short v156, v127, s[100:101] offset:128
	global_store_short_d16_hi v156, v127, s[100:101] offset:192
	v_pk_mul_f32 v[122:123], v[122:123], v[134:135] op_sel_hi:[1,0]
	v_pk_mul_f32 v[124:125], v[124:125], v[134:135] op_sel_hi:[1,0]
	v_cvt_pk_bf16_f32 v122, v122, v123
	v_cvt_pk_bf16_f32 v123, v124, v125
	global_store_short v156, v122, s[100:101] offset:1056
	global_store_short_d16_hi v156, v122, s[100:101] offset:1120
	global_store_short v156, v123, s[100:101] offset:1184
	global_store_short_d16_hi v156, v123, s[100:101] offset:1248
	s_add_u32 s100, s34, 0x100000
	s_addc_u32 s101, s35, 0
	v_pk_mul_f32 v[118:119], v[118:119], v[134:135] op_sel_hi:[1,0]
	v_pk_mul_f32 v[120:121], v[120:121], v[134:135] op_sel_hi:[1,0]
	v_cvt_pk_bf16_f32 v118, v118, v119
	v_cvt_pk_bf16_f32 v119, v120, v121
	global_store_short v156, v118, s[100:101]
	global_store_short_d16_hi v156, v118, s[100:101] offset:64
	global_store_short v156, v119, s[100:101] offset:128
	global_store_short_d16_hi v156, v119, s[100:101] offset:192
	v_pk_mul_f32 v[114:115], v[114:115], v[134:135] op_sel_hi:[1,0]
	v_pk_mul_f32 v[116:117], v[116:117], v[134:135] op_sel_hi:[1,0]
	v_cvt_pk_bf16_f32 v114, v114, v115
	v_cvt_pk_bf16_f32 v115, v116, v117
	global_store_short v156, v114, s[100:101] offset:1056
	global_store_short_d16_hi v156, v114, s[100:101] offset:1120
	global_store_short v156, v115, s[100:101] offset:1184
	global_store_short_d16_hi v156, v115, s[100:101] offset:1248
	s_mov_b64 s[100:101], s[34:35]
	v_pk_mul_f32 v[110:111], v[110:111], v[136:137] op_sel_hi:[1,0]
	v_pk_mul_f32 v[112:113], v[112:113], v[136:137] op_sel_hi:[1,0]
	v_cvt_pk_bf16_f32 v110, v110, v111
	v_cvt_pk_bf16_f32 v111, v112, v113
	global_store_short v156, v110, s[100:101] offset:32
	global_store_short_d16_hi v156, v110, s[100:101] offset:96
	global_store_short v156, v111, s[100:101] offset:160
	global_store_short_d16_hi v156, v111, s[100:101] offset:224
	v_pk_mul_f32 v[106:107], v[106:107], v[136:137] op_sel_hi:[1,0]
	v_pk_mul_f32 v[108:109], v[108:109], v[136:137] op_sel_hi:[1,0]
	v_cvt_pk_bf16_f32 v106, v106, v107
	v_cvt_pk_bf16_f32 v107, v108, v109
	global_store_short v156, v106, s[100:101] offset:1024
	global_store_short_d16_hi v156, v106, s[100:101] offset:1088
	global_store_short v156, v107, s[100:101] offset:1152
	global_store_short_d16_hi v156, v107, s[100:101] offset:1216
	s_add_u32 s100, s34, 0x100000
	s_addc_u32 s101, s35, 0
	v_pk_mul_f32 v[102:103], v[102:103], v[136:137] op_sel_hi:[1,0]
	v_pk_mul_f32 v[104:105], v[104:105], v[136:137] op_sel_hi:[1,0]
	v_cvt_pk_bf16_f32 v102, v102, v103
	v_cvt_pk_bf16_f32 v103, v104, v105
	global_store_short v156, v102, s[100:101] offset:32
	global_store_short_d16_hi v156, v102, s[100:101] offset:96
	global_store_short v156, v103, s[100:101] offset:160
	global_store_short_d16_hi v156, v103, s[100:101] offset:224
	v_pk_mul_f32 v[98:99], v[98:99], v[136:137] op_sel_hi:[1,0]
	v_pk_mul_f32 v[100:101], v[100:101], v[136:137] op_sel_hi:[1,0]
	v_cvt_pk_bf16_f32 v98, v98, v99
	v_cvt_pk_bf16_f32 v99, v100, v101
	global_store_short v156, v98, s[100:101] offset:1024
	global_store_short_d16_hi v156, v98, s[100:101] offset:1088
	global_store_short v156, v99, s[100:101] offset:1152
	global_store_short_d16_hi v156, v99, s[100:101] offset:1216
	s_add_u32 s100, s34, 0x2000
	s_addc_u32 s101, s35, 0
	v_pk_mul_f32 v[94:95], v[94:95], v[138:139] op_sel_hi:[1,0]
	v_pk_mul_f32 v[96:97], v[96:97], v[138:139] op_sel_hi:[1,0]
	v_cvt_pk_bf16_f32 v94, v94, v95
	v_cvt_pk_bf16_f32 v95, v96, v97
	global_store_short v156, v94, s[100:101]
	global_store_short_d16_hi v156, v94, s[100:101] offset:64
	global_store_short v156, v95, s[100:101] offset:128
	global_store_short_d16_hi v156, v95, s[100:101] offset:192
	v_pk_mul_f32 v[90:91], v[90:91], v[138:139] op_sel_hi:[1,0]
	v_pk_mul_f32 v[92:93], v[92:93], v[138:139] op_sel_hi:[1,0]
	v_cvt_pk_bf16_f32 v90, v90, v91
	v_cvt_pk_bf16_f32 v91, v92, v93
	global_store_short v156, v90, s[100:101] offset:1056
	global_store_short_d16_hi v156, v90, s[100:101] offset:1120
	global_store_short v156, v91, s[100:101] offset:1184
	global_store_short_d16_hi v156, v91, s[100:101] offset:1248
	s_add_u32 s100, s34, 0x102000
	s_addc_u32 s101, s35, 0
	v_pk_mul_f32 v[86:87], v[86:87], v[138:139] op_sel_hi:[1,0]
	v_pk_mul_f32 v[88:89], v[88:89], v[138:139] op_sel_hi:[1,0]
	v_cvt_pk_bf16_f32 v86, v86, v87
	v_cvt_pk_bf16_f32 v87, v88, v89
	global_store_short v156, v86, s[100:101]
	global_store_short_d16_hi v156, v86, s[100:101] offset:64
	global_store_short v156, v87, s[100:101] offset:128
	global_store_short_d16_hi v156, v87, s[100:101] offset:192
	v_pk_mul_f32 v[82:83], v[82:83], v[138:139] op_sel_hi:[1,0]
	v_pk_mul_f32 v[84:85], v[84:85], v[138:139] op_sel_hi:[1,0]
	v_cvt_pk_bf16_f32 v82, v82, v83
	v_cvt_pk_bf16_f32 v83, v84, v85
; DI bf16_t f2bf(float x) { return (bf16_t)(pk2(x, 0.f) & 0xffffu); }
; DI void st_tr4(bf16_t* p, size_t stride, f32x4 v) { p[0] = f2bf(v[0]); p[stride] = f2bf(v[1]); p[2 * stride] = f2bf(v[2]); p[3 * stride] = f2bf(v[3]); }
;   DI void one(int row, int c, f32x4 v) const {
;     ...
;       else st_tr4((bf16_t*)(ws + E_FVT) + (size_t)(b * 8 + h) * 128 * T_ + (size_t)(t >> 5) * 4096 + d * 32 + ((((t & 31) >> 2) ^ ((d >> 2) & 7)) << 2) + (t & 3), 32, v);
	global_store_short v156, v82, s[100:101] offset:1056
	global_store_short_d16_hi v156, v82, s[100:101] offset:1120
	global_store_short v156, v83, s[100:101] offset:1184
	global_store_short_d16_hi v156, v83, s[100:101] offset:1248
	s_add_u32 s100, s34, 0x2000
	s_addc_u32 s101, s35, 0
	v_pk_mul_f32 v[78:79], v[78:79], v[140:141] op_sel_hi:[1,0]
	v_pk_mul_f32 v[80:81], v[80:81], v[140:141] op_sel_hi:[1,0]
	v_cvt_pk_bf16_f32 v78, v78, v79
	v_cvt_pk_bf16_f32 v79, v80, v81
	global_store_short v156, v78, s[100:101] offset:32
	global_store_short_d16_hi v156, v78, s[100:101] offset:96
	global_store_short v156, v79, s[100:101] offset:160
	global_store_short_d16_hi v156, v79, s[100:101] offset:224
	v_pk_mul_f32 v[74:75], v[74:75], v[140:141] op_sel_hi:[1,0]
	v_pk_mul_f32 v[76:77], v[76:77], v[140:141] op_sel_hi:[1,0]
	v_cvt_pk_bf16_f32 v74, v74, v75
	v_cvt_pk_bf16_f32 v75, v76, v77
	global_store_short v156, v74, s[100:101] offset:1024
	global_store_short_d16_hi v156, v74, s[100:101] offset:1088
	global_store_short v156, v75, s[100:101] offset:1152
	global_store_short_d16_hi v156, v75, s[100:101] offset:1216
	s_add_u32 s100, s34, 0x102000
	s_addc_u32 s101, s35, 0
	v_pk_mul_f32 v[70:71], v[70:71], v[140:141] op_sel_hi:[1,0]
	v_pk_mul_f32 v[72:73], v[72:73], v[140:141] op_sel_hi:[1,0]
	v_cvt_pk_bf16_f32 v70, v70, v71
	v_cvt_pk_bf16_f32 v71, v72, v73
	global_store_short v156, v70, s[100:101] offset:32
	global_store_short_d16_hi v156, v70, s[100:101] offset:96
	global_store_short v156, v71, s[100:101] offset:160
	global_store_short_d16_hi v156, v71, s[100:101] offset:224
	v_pk_mul_f32 v[66:67], v[66:67], v[140:141] op_sel_hi:[1,0]
	v_pk_mul_f32 v[68:69], v[68:69], v[140:141] op_sel_hi:[1,0]
	v_cvt_pk_bf16_f32 v66, v66, v67
	v_cvt_pk_bf16_f32 v67, v68, v69
	global_store_short v156, v66, s[100:101] offset:1024
	global_store_short_d16_hi v156, v66, s[100:101] offset:1088
	global_store_short v156, v67, s[100:101] offset:1152
	global_store_short_d16_hi v156, v67, s[100:101] offset:1216
	s_add_u32 s100, s34, 0x8000
	s_addc_u32 s101, s35, 0
	v_pk_mul_f32 v[62:63], v[62:63], v[142:143] op_sel_hi:[1,0]
	v_pk_mul_f32 v[64:65], v[64:65], v[142:143] op_sel_hi:[1,0]
	v_cvt_pk_bf16_f32 v62, v62, v63
	v_cvt_pk_bf16_f32 v63, v64, v65
	global_store_short v156, v62, s[100:101]
	global_store_short_d16_hi v156, v62, s[100:101] offset:64
	global_store_short v156, v63, s[100:101] offset:128
	global_store_short_d16_hi v156, v63, s[100:101] offset:192
	v_pk_mul_f32 v[58:59], v[58:59], v[142:143] op_sel_hi:[1,0]
	v_pk_mul_f32 v[60:61], v[60:61], v[142:143] op_sel_hi:[1,0]
	v_cvt_pk_bf16_f32 v58, v58, v59
	v_cvt_pk_bf16_f32 v59, v60, v61
	global_store_short v156, v58, s[100:101] offset:1056
	global_store_short_d16_hi v156, v58, s[100:101] offset:1120
	global_store_short v156, v59, s[100:101] offset:1184
	global_store_short_d16_hi v156, v59, s[100:101] offset:1248
	s_add_u32 s100, s34, 0x108000
	s_addc_u32 s101, s35, 0
	v_pk_mul_f32 v[54:55], v[54:55], v[142:143] op_sel_hi:[1,0]
	v_pk_mul_f32 v[56:57], v[56:57], v[142:143] op_sel_hi:[1,0]
	v_cvt_pk_bf16_f32 v54, v54, v55
	v_cvt_pk_bf16_f32 v55, v56, v57
	global_store_short v156, v54, s[100:101]
	global_store_short_d16_hi v156, v54, s[100:101] offset:64
	global_store_short v156, v55, s[100:101] offset:128
	global_store_short_d16_hi v156, v55, s[100:101] offset:192
	v_pk_mul_f32 v[50:51], v[50:51], v[142:143] op_sel_hi:[1,0]
	v_pk_mul_f32 v[52:53], v[52:53], v[142:143] op_sel_hi:[1,0]
	v_cvt_pk_bf16_f32 v50, v50, v51
	v_cvt_pk_bf16_f32 v51, v52, v53
	global_store_short v156, v50, s[100:101] offset:1056
	global_store_short_d16_hi v156, v50, s[100:101] offset:1120
	global_store_short v156, v51, s[100:101] offset:1184
	global_store_short_d16_hi v156, v51, s[100:101] offset:1248
	s_add_u32 s100, s34, 0x8000
	s_addc_u32 s101, s35, 0
	v_pk_mul_f32 v[46:47], v[46:47], v[146:147] op_sel_hi:[1,0]
	v_pk_mul_f32 v[48:49], v[48:49], v[146:147] op_sel_hi:[1,0]
	v_cvt_pk_bf16_f32 v46, v46, v47
	v_cvt_pk_bf16_f32 v47, v48, v49
	global_store_short v156, v46, s[100:101] offset:32
	global_store_short_d16_hi v156, v46, s[100:101] offset:96
	global_store_short v156, v47, s[100:101] offset:160
	global_store_short_d16_hi v156, v47, s[100:101] offset:224
	v_pk_mul_f32 v[42:43], v[42:43], v[146:147] op_sel_hi:[1,0]
	v_pk_mul_f32 v[44:45], v[44:45], v[146:147] op_sel_hi:[1,0]
	v_cvt_pk_bf16_f32 v42, v42, v43
	v_cvt_pk_bf16_f32 v43, v44, v45
	global_store_short v156, v42, s[100:101] offset:1024
	global_store_short_d16_hi v156, v42, s[100:101] offset:1088
	global_store_short v156, v43, s[100:101] offset:1152
	global_store_short_d16_hi v156, v43, s[100:101] offset:1216
	s_add_u32 s100, s34, 0x108000
	s_addc_u32 s101, s35, 0
	v_pk_mul_f32 v[38:39], v[38:39], v[146:147] op_sel_hi:[1,0]
	v_pk_mul_f32 v[40:41], v[40:41], v[146:147] op_sel_hi:[1,0]
	v_cvt_pk_bf16_f32 v38, v38, v39
	v_cvt_pk_bf16_f32 v39, v40, v41
	global_store_short v156, v38, s[100:101] offset:32
	global_store_short_d16_hi v156, v38, s[100:101] offset:96
	global_store_short v156, v39, s[100:101] offset:160
	global_store_short_d16_hi v156, v39, s[100:101] offset:224
	v_pk_mul_f32 v[34:35], v[34:35], v[146:147] op_sel_hi:[1,0]
	v_pk_mul_f32 v[36:37], v[36:37], v[146:147] op_sel_hi:[1,0]
	v_cvt_pk_bf16_f32 v34, v34, v35
	v_cvt_pk_bf16_f32 v35, v36, v37
	global_store_short v156, v34, s[100:101] offset:1024
	global_store_short_d16_hi v156, v34, s[100:101] offset:1088
	global_store_short v156, v35, s[100:101] offset:1152
	global_store_short_d16_hi v156, v35, s[100:101] offset:1216
	s_add_u32 s100, s34, 0xa000
	s_addc_u32 s101, s35, 0
	v_pk_mul_f32 v[30:31], v[30:31], v[150:151] op_sel_hi:[1,0]
; DI bf16_t f2bf(float x) { return (bf16_t)(pk2(x, 0.f) & 0xffffu); }
; DI void st_tr4(bf16_t* p, size_t stride, f32x4 v) { p[0] = f2bf(v[0]); p[stride] = f2bf(v[1]); p[2 * stride] = f2bf(v[2]); p[3 * stride] = f2bf(v[3]); }
;   DI void one(int row, int c, f32x4 v) const {
;     ...
;       else st_tr4((bf16_t*)(ws + E_FVT) + (size_t)(b * 8 + h) * 128 * T_ + (size_t)(t >> 5) * 4096 + d * 32 + ((((t & 31) >> 2) ^ ((d >> 2) & 7)) << 2) + (t & 3), 32, v);
;     ...
;     } else if (c < 6144) { const int cc = c - 5120, h = cc >> 7, d = cc & 127; st_tr4((bf16_t*)(ws + E_HIT) + (size_t)(b * 8 + h) * 128 * T_ + (size_t)(t >> 5) * 4096 + d * 32 + (t & 31), 32, v);
	v_pk_mul_f32 v[32:33], v[32:33], v[150:151] op_sel_hi:[1,0]
	v_cvt_pk_bf16_f32 v30, v30, v31
	v_cvt_pk_bf16_f32 v31, v32, v33
	global_store_short v156, v30, s[100:101]
	global_store_short_d16_hi v156, v30, s[100:101] offset:64
	global_store_short v156, v31, s[100:101] offset:128
	global_store_short_d16_hi v156, v31, s[100:101] offset:192
	v_pk_mul_f32 v[26:27], v[26:27], v[150:151] op_sel_hi:[1,0]
	v_pk_mul_f32 v[28:29], v[28:29], v[150:151] op_sel_hi:[1,0]
	v_cvt_pk_bf16_f32 v26, v26, v27
	v_cvt_pk_bf16_f32 v27, v28, v29
	global_store_short v156, v26, s[100:101] offset:1056
	global_store_short_d16_hi v156, v26, s[100:101] offset:1120
	global_store_short v156, v27, s[100:101] offset:1184
	global_store_short_d16_hi v156, v27, s[100:101] offset:1248
	s_add_u32 s100, s34, 0x10a000
	s_addc_u32 s101, s35, 0
	v_pk_mul_f32 v[22:23], v[22:23], v[150:151] op_sel_hi:[1,0]
	v_pk_mul_f32 v[24:25], v[24:25], v[150:151] op_sel_hi:[1,0]
	v_cvt_pk_bf16_f32 v22, v22, v23
	v_cvt_pk_bf16_f32 v23, v24, v25
	global_store_short v156, v22, s[100:101]
	global_store_short_d16_hi v156, v22, s[100:101] offset:64
	global_store_short v156, v23, s[100:101] offset:128
	global_store_short_d16_hi v156, v23, s[100:101] offset:192
	v_pk_mul_f32 v[18:19], v[18:19], v[150:151] op_sel_hi:[1,0]
	v_pk_mul_f32 v[20:21], v[20:21], v[150:151] op_sel_hi:[1,0]
	v_cvt_pk_bf16_f32 v18, v18, v19
	v_cvt_pk_bf16_f32 v19, v20, v21
	global_store_short v156, v18, s[100:101] offset:1056
	global_store_short_d16_hi v156, v18, s[100:101] offset:1120
	global_store_short v156, v19, s[100:101] offset:1184
	global_store_short_d16_hi v156, v19, s[100:101] offset:1248
	s_add_u32 s100, s34, 0xa000
	s_addc_u32 s101, s35, 0
	v_pk_mul_f32 v[14:15], v[14:15], v[154:155] op_sel_hi:[1,0]
	v_pk_mul_f32 v[16:17], v[16:17], v[154:155] op_sel_hi:[1,0]
	v_cvt_pk_bf16_f32 v14, v14, v15
	v_cvt_pk_bf16_f32 v15, v16, v17
	global_store_short v156, v14, s[100:101] offset:32
	global_store_short_d16_hi v156, v14, s[100:101] offset:96
	global_store_short v156, v15, s[100:101] offset:160
	global_store_short_d16_hi v156, v15, s[100:101] offset:224
	v_pk_mul_f32 v[10:11], v[10:11], v[154:155] op_sel_hi:[1,0]
	v_pk_mul_f32 v[12:13], v[12:13], v[154:155] op_sel_hi:[1,0]
	v_cvt_pk_bf16_f32 v10, v10, v11
	v_cvt_pk_bf16_f32 v11, v12, v13
	global_store_short v156, v10, s[100:101] offset:1024
	global_store_short_d16_hi v156, v10, s[100:101] offset:1088
	global_store_short v156, v11, s[100:101] offset:1152
	global_store_short_d16_hi v156, v11, s[100:101] offset:1216
	s_add_u32 s100, s34, 0x10a000
	s_addc_u32 s101, s35, 0
	v_pk_mul_f32 v[6:7], v[6:7], v[154:155] op_sel_hi:[1,0]
	v_pk_mul_f32 v[8:9], v[8:9], v[154:155] op_sel_hi:[1,0]
	v_cvt_pk_bf16_f32 v6, v6, v7
	v_cvt_pk_bf16_f32 v7, v8, v9
	global_store_short v156, v6, s[100:101] offset:32
	global_store_short_d16_hi v156, v6, s[100:101] offset:96
	global_store_short v156, v7, s[100:101] offset:160
	global_store_short_d16_hi v156, v7, s[100:101] offset:224
	v_pk_mul_f32 v[2:3], v[2:3], v[154:155] op_sel_hi:[1,0]
	v_pk_mul_f32 v[4:5], v[4:5], v[154:155] op_sel_hi:[1,0]
	v_cvt_pk_bf16_f32 v2, v2, v3
	v_cvt_pk_bf16_f32 v3, v4, v5
	global_store_short v156, v2, s[100:101] offset:1024
	global_store_short_d16_hi v156, v2, s[100:101] offset:1088
	global_store_short v156, v3, s[100:101] offset:1152
	global_store_short_d16_hi v156, v3, s[100:101] offset:1216
	s_branch .Lepe_done
.Lepe_dpl:
	s_lshl_b32 s16, s11, 3
	s_lshl_b32 s17, s14, 1
	s_add_i32 s16, s16, s17
	s_lshl_b32 s16, s16, 20
	s_add_i32 s16, s16, s12
	s_add_u32 s16, s16, 0x2b145000
	s_add_u32 s34, s30, s16
	s_addc_u32 s35, s31, 0
	v_mov_b32_e32 v156, v157
	v_lshlrev_b32_e32 v156, 1, v156
	v_lshl_add_u32 v156, v158, 8, v156
	s_lshl_b32 s17, s22, 8
	s_lshl_b32 s16, s23, 6
	s_add_i32 s17, s17, s16
	v_add_u32_e32 v156, s17, v156
	s_mov_b64 s[100:101], s[34:35]
	v_pk_mul_f32 v[126:127], v[126:127], v[134:135] op_sel_hi:[1,0]
	v_pk_mul_f32 v[128:129], v[128:129], v[134:135] op_sel_hi:[1,0]
	v_cvt_pk_bf16_f32 v126, v126, v127
	v_cvt_pk_bf16_f32 v127, v128, v129
	global_store_short v156, v126, s[100:101]
	global_store_short_d16_hi v156, v126, s[100:101] offset:64
	global_store_short v156, v127, s[100:101] offset:128
	global_store_short_d16_hi v156, v127, s[100:101] offset:192
	v_pk_mul_f32 v[122:123], v[122:123], v[134:135] op_sel_hi:[1,0]
	v_pk_mul_f32 v[124:125], v[124:125], v[134:135] op_sel_hi:[1,0]
	v_cvt_pk_bf16_f32 v122, v122, v123
	v_cvt_pk_bf16_f32 v123, v124, v125
	global_store_short v156, v122, s[100:101] offset:1024
	global_store_short_d16_hi v156, v122, s[100:101] offset:1088
	global_store_short v156, v123, s[100:101] offset:1152
	global_store_short_d16_hi v156, v123, s[100:101] offset:1216
	s_add_u32 s100, s34, 0x100000
	s_addc_u32 s101, s35, 0
	v_pk_mul_f32 v[118:119], v[118:119], v[134:135] op_sel_hi:[1,0]
	v_pk_mul_f32 v[120:121], v[120:121], v[134:135] op_sel_hi:[1,0]
	v_cvt_pk_bf16_f32 v118, v118, v119
	v_cvt_pk_bf16_f32 v119, v120, v121
	global_store_short v156, v118, s[100:101]
	global_store_short_d16_hi v156, v118, s[100:101] offset:64
	global_store_short v156, v119, s[100:101] offset:128
	global_store_short_d16_hi v156, v119, s[100:101] offset:192
	v_pk_mul_f32 v[114:115], v[114:115], v[134:135] op_sel_hi:[1,0]
	v_pk_mul_f32 v[116:117], v[116:117], v[134:135] op_sel_hi:[1,0]
	v_cvt_pk_bf16_f32 v114, v114, v115
	v_cvt_pk_bf16_f32 v115, v116, v117
	global_store_short v156, v114, s[100:101] offset:1024
	global_store_short_d16_hi v156, v114, s[100:101] offset:1088
	global_store_short v156, v115, s[100:101] offset:1152
	global_store_short_d16_hi v156, v115, s[100:101] offset:1216
	s_mov_b64 s[100:101], s[34:35]
; DI bf16_t f2bf(float x) { return (bf16_t)(pk2(x, 0.f) & 0xffffu); }
; DI void st_tr4(bf16_t* p, size_t stride, f32x4 v) { p[0] = f2bf(v[0]); p[stride] = f2bf(v[1]); p[2 * stride] = f2bf(v[2]); p[3 * stride] = f2bf(v[3]); }
;   DI void one(int row, int c, f32x4 v) const {
;     ...
;     } else if (c < 6144) { const int cc = c - 5120, h = cc >> 7, d = cc & 127; st_tr4((bf16_t*)(ws + E_HIT) + (size_t)(b * 8 + h) * 128 * T_ + (size_t)(t >> 5) * 4096 + d * 32 + (t & 31), 32, v);
	v_pk_mul_f32 v[110:111], v[110:111], v[136:137] op_sel_hi:[1,0]
	v_pk_mul_f32 v[112:113], v[112:113], v[136:137] op_sel_hi:[1,0]
	v_cvt_pk_bf16_f32 v110, v110, v111
	v_cvt_pk_bf16_f32 v111, v112, v113
	global_store_short v156, v110, s[100:101] offset:32
	global_store_short_d16_hi v156, v110, s[100:101] offset:96
	global_store_short v156, v111, s[100:101] offset:160
	global_store_short_d16_hi v156, v111, s[100:101] offset:224
	v_pk_mul_f32 v[106:107], v[106:107], v[136:137] op_sel_hi:[1,0]
	v_pk_mul_f32 v[108:109], v[108:109], v[136:137] op_sel_hi:[1,0]
	v_cvt_pk_bf16_f32 v106, v106, v107
	v_cvt_pk_bf16_f32 v107, v108, v109
	global_store_short v156, v106, s[100:101] offset:1056
	global_store_short_d16_hi v156, v106, s[100:101] offset:1120
	global_store_short v156, v107, s[100:101] offset:1184
	global_store_short_d16_hi v156, v107, s[100:101] offset:1248
	s_add_u32 s100, s34, 0x100000
	s_addc_u32 s101, s35, 0
	v_pk_mul_f32 v[102:103], v[102:103], v[136:137] op_sel_hi:[1,0]
	v_pk_mul_f32 v[104:105], v[104:105], v[136:137] op_sel_hi:[1,0]
	v_cvt_pk_bf16_f32 v102, v102, v103
	v_cvt_pk_bf16_f32 v103, v104, v105
	global_store_short v156, v102, s[100:101] offset:32
	global_store_short_d16_hi v156, v102, s[100:101] offset:96
	global_store_short v156, v103, s[100:101] offset:160
	global_store_short_d16_hi v156, v103, s[100:101] offset:224
	v_pk_mul_f32 v[98:99], v[98:99], v[136:137] op_sel_hi:[1,0]
	v_pk_mul_f32 v[100:101], v[100:101], v[136:137] op_sel_hi:[1,0]
	v_cvt_pk_bf16_f32 v98, v98, v99
	v_cvt_pk_bf16_f32 v99, v100, v101
	global_store_short v156, v98, s[100:101] offset:1056
	global_store_short_d16_hi v156, v98, s[100:101] offset:1120
	global_store_short v156, v99, s[100:101] offset:1184
	global_store_short_d16_hi v156, v99, s[100:101] offset:1248
	s_add_u32 s100, s34, 0x2000
	s_addc_u32 s101, s35, 0
	v_pk_mul_f32 v[94:95], v[94:95], v[138:139] op_sel_hi:[1,0]
	v_pk_mul_f32 v[96:97], v[96:97], v[138:139] op_sel_hi:[1,0]
	v_cvt_pk_bf16_f32 v94, v94, v95
	v_cvt_pk_bf16_f32 v95, v96, v97
	global_store_short v156, v94, s[100:101]
	global_store_short_d16_hi v156, v94, s[100:101] offset:64
	global_store_short v156, v95, s[100:101] offset:128
	global_store_short_d16_hi v156, v95, s[100:101] offset:192
	v_pk_mul_f32 v[90:91], v[90:91], v[138:139] op_sel_hi:[1,0]
	v_pk_mul_f32 v[92:93], v[92:93], v[138:139] op_sel_hi:[1,0]
	v_cvt_pk_bf16_f32 v90, v90, v91
	v_cvt_pk_bf16_f32 v91, v92, v93
	global_store_short v156, v90, s[100:101] offset:1024
	global_store_short_d16_hi v156, v90, s[100:101] offset:1088
	global_store_short v156, v91, s[100:101] offset:1152
	global_store_short_d16_hi v156, v91, s[100:101] offset:1216
	s_add_u32 s100, s34, 0x102000
	s_addc_u32 s101, s35, 0
	v_pk_mul_f32 v[86:87], v[86:87], v[138:139] op_sel_hi:[1,0]
	v_pk_mul_f32 v[88:89], v[88:89], v[138:139] op_sel_hi:[1,0]
	v_cvt_pk_bf16_f32 v86, v86, v87
	v_cvt_pk_bf16_f32 v87, v88, v89
	global_store_short v156, v86, s[100:101]
	global_store_short_d16_hi v156, v86, s[100:101] offset:64
	global_store_short v156, v87, s[100:101] offset:128
	global_store_short_d16_hi v156, v87, s[100:101] offset:192
	v_pk_mul_f32 v[82:83], v[82:83], v[138:139] op_sel_hi:[1,0]
	v_pk_mul_f32 v[84:85], v[84:85], v[138:139] op_sel_hi:[1,0]
	v_cvt_pk_bf16_f32 v82, v82, v83
	v_cvt_pk_bf16_f32 v83, v84, v85
	global_store_short v156, v82, s[100:101] offset:1024
	global_store_short_d16_hi v156, v82, s[100:101] offset:1088
	global_store_short v156, v83, s[100:101] offset:1152
	global_store_short_d16_hi v156, v83, s[100:101] offset:1216
	s_add_u32 s100, s34, 0x2000
	s_addc_u32 s101, s35, 0
	v_pk_mul_f32 v[78:79], v[78:79], v[140:141] op_sel_hi:[1,0]
	v_pk_mul_f32 v[80:81], v[80:81], v[140:141] op_sel_hi:[1,0]
	v_cvt_pk_bf16_f32 v78, v78, v79
	v_cvt_pk_bf16_f32 v79, v80, v81
	global_store_short v156, v78, s[100:101] offset:32
	global_store_short_d16_hi v156, v78, s[100:101] offset:96
	global_store_short v156, v79, s[100:101] offset:160
	global_store_short_d16_hi v156, v79, s[100:101] offset:224
	v_pk_mul_f32 v[74:75], v[74:75], v[140:141] op_sel_hi:[1,0]
	v_pk_mul_f32 v[76:77], v[76:77], v[140:141] op_sel_hi:[1,0]
	v_cvt_pk_bf16_f32 v74, v74, v75
	v_cvt_pk_bf16_f32 v75, v76, v77
	global_store_short v156, v74, s[100:101] offset:1056
	global_store_short_d16_hi v156, v74, s[100:101] offset:1120
	global_store_short v156, v75, s[100:101] offset:1184
	global_store_short_d16_hi v156, v75, s[100:101] offset:1248
	s_add_u32 s100, s34, 0x102000
	s_addc_u32 s101, s35, 0
	v_pk_mul_f32 v[70:71], v[70:71], v[140:141] op_sel_hi:[1,0]
	v_pk_mul_f32 v[72:73], v[72:73], v[140:141] op_sel_hi:[1,0]
	v_cvt_pk_bf16_f32 v70, v70, v71
	v_cvt_pk_bf16_f32 v71, v72, v73
	global_store_short v156, v70, s[100:101] offset:32
	global_store_short_d16_hi v156, v70, s[100:101] offset:96
	global_store_short v156, v71, s[100:101] offset:160
	global_store_short_d16_hi v156, v71, s[100:101] offset:224
	v_pk_mul_f32 v[66:67], v[66:67], v[140:141] op_sel_hi:[1,0]
	v_pk_mul_f32 v[68:69], v[68:69], v[140:141] op_sel_hi:[1,0]
	v_cvt_pk_bf16_f32 v66, v66, v67
	v_cvt_pk_bf16_f32 v67, v68, v69
	global_store_short v156, v66, s[100:101] offset:1056
	global_store_short_d16_hi v156, v66, s[100:101] offset:1120
	global_store_short v156, v67, s[100:101] offset:1184
	global_store_short_d16_hi v156, v67, s[100:101] offset:1248
	s_add_u32 s100, s34, 0x8000
	s_addc_u32 s101, s35, 0
	v_pk_mul_f32 v[62:63], v[62:63], v[142:143] op_sel_hi:[1,0]
	v_pk_mul_f32 v[64:65], v[64:65], v[142:143] op_sel_hi:[1,0]
	v_cvt_pk_bf16_f32 v62, v62, v63
	v_cvt_pk_bf16_f32 v63, v64, v65
	global_store_short v156, v62, s[100:101]
	global_store_short_d16_hi v156, v62, s[100:101] offset:64
; DI bf16_t f2bf(float x) { return (bf16_t)(pk2(x, 0.f) & 0xffffu); }
; DI void st_tr4(bf16_t* p, size_t stride, f32x4 v) { p[0] = f2bf(v[0]); p[stride] = f2bf(v[1]); p[2 * stride] = f2bf(v[2]); p[3 * stride] = f2bf(v[3]); }
;   DI void one(int row, int c, f32x4 v) const {
;     ...
;     } else if (c < 6144) { const int cc = c - 5120, h = cc >> 7, d = cc & 127; st_tr4((bf16_t*)(ws + E_HIT) + (size_t)(b * 8 + h) * 128 * T_ + (size_t)(t >> 5) * 4096 + d * 32 + (t & 31), 32, v);
	global_store_short v156, v63, s[100:101] offset:128
	global_store_short_d16_hi v156, v63, s[100:101] offset:192
	v_pk_mul_f32 v[58:59], v[58:59], v[142:143] op_sel_hi:[1,0]
	v_pk_mul_f32 v[60:61], v[60:61], v[142:143] op_sel_hi:[1,0]
	v_cvt_pk_bf16_f32 v58, v58, v59
	v_cvt_pk_bf16_f32 v59, v60, v61
	global_store_short v156, v58, s[100:101] offset:1024
	global_store_short_d16_hi v156, v58, s[100:101] offset:1088
	global_store_short v156, v59, s[100:101] offset:1152
	global_store_short_d16_hi v156, v59, s[100:101] offset:1216
	s_add_u32 s100, s34, 0x108000
	s_addc_u32 s101, s35, 0
	v_pk_mul_f32 v[54:55], v[54:55], v[142:143] op_sel_hi:[1,0]
	v_pk_mul_f32 v[56:57], v[56:57], v[142:143] op_sel_hi:[1,0]
	v_cvt_pk_bf16_f32 v54, v54, v55
	v_cvt_pk_bf16_f32 v55, v56, v57
	global_store_short v156, v54, s[100:101]
	global_store_short_d16_hi v156, v54, s[100:101] offset:64
	global_store_short v156, v55, s[100:101] offset:128
	global_store_short_d16_hi v156, v55, s[100:101] offset:192
	v_pk_mul_f32 v[50:51], v[50:51], v[142:143] op_sel_hi:[1,0]
	v_pk_mul_f32 v[52:53], v[52:53], v[142:143] op_sel_hi:[1,0]
	v_cvt_pk_bf16_f32 v50, v50, v51
	v_cvt_pk_bf16_f32 v51, v52, v53
	global_store_short v156, v50, s[100:101] offset:1024
	global_store_short_d16_hi v156, v50, s[100:101] offset:1088
	global_store_short v156, v51, s[100:101] offset:1152
	global_store_short_d16_hi v156, v51, s[100:101] offset:1216
	s_add_u32 s100, s34, 0x8000
	s_addc_u32 s101, s35, 0
	v_pk_mul_f32 v[46:47], v[46:47], v[146:147] op_sel_hi:[1,0]
	v_pk_mul_f32 v[48:49], v[48:49], v[146:147] op_sel_hi:[1,0]
	v_cvt_pk_bf16_f32 v46, v46, v47
	v_cvt_pk_bf16_f32 v47, v48, v49
	global_store_short v156, v46, s[100:101] offset:32
	global_store_short_d16_hi v156, v46, s[100:101] offset:96
	global_store_short v156, v47, s[100:101] offset:160
	global_store_short_d16_hi v156, v47, s[100:101] offset:224
	v_pk_mul_f32 v[42:43], v[42:43], v[146:147] op_sel_hi:[1,0]
	v_pk_mul_f32 v[44:45], v[44:45], v[146:147] op_sel_hi:[1,0]
	v_cvt_pk_bf16_f32 v42, v42, v43
	v_cvt_pk_bf16_f32 v43, v44, v45
	global_store_short v156, v42, s[100:101] offset:1056
	global_store_short_d16_hi v156, v42, s[100:101] offset:1120
	global_store_short v156, v43, s[100:101] offset:1184
	global_store_short_d16_hi v156, v43, s[100:101] offset:1248
	s_add_u32 s100, s34, 0x108000
	s_addc_u32 s101, s35, 0
	v_pk_mul_f32 v[38:39], v[38:39], v[146:147] op_sel_hi:[1,0]
	v_pk_mul_f32 v[40:41], v[40:41], v[146:147] op_sel_hi:[1,0]
	v_cvt_pk_bf16_f32 v38, v38, v39
	v_cvt_pk_bf16_f32 v39, v40, v41
	global_store_short v156, v38, s[100:101] offset:32
	global_store_short_d16_hi v156, v38, s[100:101] offset:96
	global_store_short v156, v39, s[100:101] offset:160
	global_store_short_d16_hi v156, v39, s[100:101] offset:224
	v_pk_mul_f32 v[34:35], v[34:35], v[146:147] op_sel_hi:[1,0]
	v_pk_mul_f32 v[36:37], v[36:37], v[146:147] op_sel_hi:[1,0]
	v_cvt_pk_bf16_f32 v34, v34, v35
	v_cvt_pk_bf16_f32 v35, v36, v37
	global_store_short v156, v34, s[100:101] offset:1056
	global_store_short_d16_hi v156, v34, s[100:101] offset:1120
	global_store_short v156, v35, s[100:101] offset:1184
	global_store_short_d16_hi v156, v35, s[100:101] offset:1248
	s_add_u32 s100, s34, 0xa000
	s_addc_u32 s101, s35, 0
	v_pk_mul_f32 v[30:31], v[30:31], v[150:151] op_sel_hi:[1,0]
	v_pk_mul_f32 v[32:33], v[32:33], v[150:151] op_sel_hi:[1,0]
	v_cvt_pk_bf16_f32 v30, v30, v31
	v_cvt_pk_bf16_f32 v31, v32, v33
	global_store_short v156, v30, s[100:101]
	global_store_short_d16_hi v156, v30, s[100:101] offset:64
	global_store_short v156, v31, s[100:101] offset:128
	global_store_short_d16_hi v156, v31, s[100:101] offset:192
	v_pk_mul_f32 v[26:27], v[26:27], v[150:151] op_sel_hi:[1,0]
	v_pk_mul_f32 v[28:29], v[28:29], v[150:151] op_sel_hi:[1,0]
	v_cvt_pk_bf16_f32 v26, v26, v27
	v_cvt_pk_bf16_f32 v27, v28, v29
	global_store_short v156, v26, s[100:101] offset:1024
	global_store_short_d16_hi v156, v26, s[100:101] offset:1088
	global_store_short v156, v27, s[100:101] offset:1152
	global_store_short_d16_hi v156, v27, s[100:101] offset:1216
	s_add_u32 s100, s34, 0x10a000
	s_addc_u32 s101, s35, 0
	v_pk_mul_f32 v[22:23], v[22:23], v[150:151] op_sel_hi:[1,0]
	v_pk_mul_f32 v[24:25], v[24:25], v[150:151] op_sel_hi:[1,0]
	v_cvt_pk_bf16_f32 v22, v22, v23
	v_cvt_pk_bf16_f32 v23, v24, v25
	global_store_short v156, v22, s[100:101]
	global_store_short_d16_hi v156, v22, s[100:101] offset:64
	global_store_short v156, v23, s[100:101] offset:128
	global_store_short_d16_hi v156, v23, s[100:101] offset:192
	v_pk_mul_f32 v[18:19], v[18:19], v[150:151] op_sel_hi:[1,0]
	v_pk_mul_f32 v[20:21], v[20:21], v[150:151] op_sel_hi:[1,0]
	v_cvt_pk_bf16_f32 v18, v18, v19
	v_cvt_pk_bf16_f32 v19, v20, v21
	global_store_short v156, v18, s[100:101] offset:1024
	global_store_short_d16_hi v156, v18, s[100:101] offset:1088
	global_store_short v156, v19, s[100:101] offset:1152
	global_store_short_d16_hi v156, v19, s[100:101] offset:1216
	s_add_u32 s100, s34, 0xa000
	s_addc_u32 s101, s35, 0
	v_pk_mul_f32 v[14:15], v[14:15], v[154:155] op_sel_hi:[1,0]
	v_pk_mul_f32 v[16:17], v[16:17], v[154:155] op_sel_hi:[1,0]
	v_cvt_pk_bf16_f32 v14, v14, v15
	v_cvt_pk_bf16_f32 v15, v16, v17
	global_store_short v156, v14, s[100:101] offset:32
	global_store_short_d16_hi v156, v14, s[100:101] offset:96
	global_store_short v156, v15, s[100:101] offset:160
	global_store_short_d16_hi v156, v15, s[100:101] offset:224
	v_pk_mul_f32 v[10:11], v[10:11], v[154:155] op_sel_hi:[1,0]
	v_pk_mul_f32 v[12:13], v[12:13], v[154:155] op_sel_hi:[1,0]
	v_cvt_pk_bf16_f32 v10, v10, v11
	v_cvt_pk_bf16_f32 v11, v12, v13
	global_store_short v156, v10, s[100:101] offset:1056
	global_store_short_d16_hi v156, v10, s[100:101] offset:1120
	global_store_short v156, v11, s[100:101] offset:1184
	global_store_short_d16_hi v156, v11, s[100:101] offset:1248
	s_add_u32 s100, s34, 0x10a000
	s_addc_u32 s101, s35, 0
	v_pk_mul_f32 v[6:7], v[6:7], v[154:155] op_sel_hi:[1,0]
	v_pk_mul_f32 v[8:9], v[8:9], v[154:155] op_sel_hi:[1,0]
	v_cvt_pk_bf16_f32 v6, v6, v7
	v_cvt_pk_bf16_f32 v7, v8, v9
	global_store_short v156, v6, s[100:101] offset:32
	global_store_short_d16_hi v156, v6, s[100:101] offset:96
	global_store_short v156, v7, s[100:101] offset:160
	global_store_short_d16_hi v156, v7, s[100:101] offset:224
	v_pk_mul_f32 v[2:3], v[2:3], v[154:155] op_sel_hi:[1,0]
	v_pk_mul_f32 v[4:5], v[4:5], v[154:155] op_sel_hi:[1,0]
	v_cvt_pk_bf16_f32 v2, v2, v3
	v_cvt_pk_bf16_f32 v3, v4, v5
	global_store_short v156, v2, s[100:101] offset:1056
	global_store_short_d16_hi v156, v2, s[100:101] offset:1120
	global_store_short v156, v3, s[100:101] offset:1184
	global_store_short_d16_hi v156, v3, s[100:101] offset:1248
	s_branch .Lepe_done
; DI void st_bf16x4(bf16_t* p, f32x4 v) { u32x2 o; o.x = pk2e(v[0], v[1]); o.y = pk2e(v[2], v[3]); *(u32x2*)p = o; }
; DI void st_tr4(bf16_t* p, size_t stride, f32x4 v) { p[0] = f2bf(v[0]); p[stride] = f2bf(v[1]); p[2 * stride] = f2bf(v[2]); p[3 * stride] = f2bf(v[3]); }
;   DI float operator()(int row, int colbase, int fq, f32x4 v0, f32x4 v1) const { one(row, colbase + 4 * fq, v0); one(row, colbase + 16 + 4 * fq, v1); return 0.f; }
;   DI float operator()(int row, int colbase, int fq, f32x4 v0, f32x4 v1) const { one(row, colbase + 4 * fq, v0); one(row, colbase + 16 + 4 * fq, v1); return 0.f; }
;   DI float operator()(int row, int colbase, int fq, f32x4 v0, f32x4 v1) const { one(row, colbase + 4 * fq, v0); one(row, colbase + 16 + 4 * fq, v1); return 0.f; }
;   DI void one(int row, int c, f32x4 v) const {
;     const int b = row >> 12, t = row & 4095;
;     if (c < 3072) {
;       const int seg = c >> 10, cc = c & 1023, h = cc >> 7, d = cc & 127;
;       if (seg < 2) st_bf16x4((bf16_t*)(ws + (seg == 0 ? E_FQ : E_FK)) + ((size_t)(b * 8 + h) * T_ + t) * 128 + d, v);
;       else st_tr4((bf16_t*)(ws + E_FVT) + (size_t)(b * 8 + h) * 128 * T_ + (size_t)(t >> 5) * 4096 + d * 32 + ((((t & 31) >> 2) ^ ((d >> 2) & 7)) << 2) + (t & 3), 32, v);
;     } else if (c < 4096) { st_bf16x4((bf16_t*)(ws + E_HQ) + (size_t)row * 1024 + (c - 3072), v);
;     } else if (c < 5120) { *(f32x4*)((float*)(ws + E_HF) + (size_t)row * 1024 + (c - 4096)) = v;
;     } else if (c < 6144) { const int cc = c - 5120, h = cc >> 7, d = cc & 127; st_tr4((bf16_t*)(ws + E_HIT) + (size_t)(b * 8 + h) * 128 * T_ + (size_t)(t >> 5) * 4096 + d * 32 + (t & 31), 32, v);
;     } else if (c < 7168) { st_bf16x4((bf16_t*)(ws + E_HG) + (size_t)row * 1024 + (c - 6144), v);
;     } else if (c < 7176) { *(f32x4*)((float*)(ws + E_FF) + (size_t)row * 8 + (c - 7168)) = v; }
;   }
;   DI float operator()(int row, int colbase, int fq, f32x4 v0, f32x4 v1) const { one(row, colbase + 4 * fq, v0); one(row, colbase + 16 + 4 * fq, v1); return 0.f; }
.Lepe_c:
	s_lshl_b32 s16, s9, 12
	s_lshl_b32 s17, s14, 10
	s_add_i32 s16, s16, s17
	s_add_u32 s16, s16, 0x29145000
	s_add_u32 s34, s30, s16
	s_addc_u32 s35, s31, 0
	v_lshlrev_b32_e32 v156, 12, v157
	v_lshl_add_u32 v156, v158, 4, v156
	s_lshl_b32 s17, s22, 12
	s_lshl_b32 s16, s23, 2
	s_add_i32 s17, s17, s16
	v_add_u32_e32 v156, s17, v156
	s_mov_b64 s[100:101], s[34:35]
	v_pk_mul_f32 v[126:127], v[126:127], v[134:135] op_sel_hi:[1,0]
	v_pk_mul_f32 v[128:129], v[128:129], v[134:135] op_sel_hi:[1,0]
	global_store_dwordx4 v156, v[126:129], s[100:101]
	v_pk_mul_f32 v[122:123], v[122:123], v[134:135] op_sel_hi:[1,0]
	v_pk_mul_f32 v[124:125], v[124:125], v[134:135] op_sel_hi:[1,0]
	global_store_dwordx4 v156, v[122:125], s[100:101] offset:64
	v_pk_mul_f32 v[118:119], v[118:119], v[134:135] op_sel_hi:[1,0]
	v_pk_mul_f32 v[120:121], v[120:121], v[134:135] op_sel_hi:[1,0]
	global_store_dwordx4 v156, v[118:121], s[100:101] offset:512
	v_pk_mul_f32 v[114:115], v[114:115], v[134:135] op_sel_hi:[1,0]
	v_pk_mul_f32 v[116:117], v[116:117], v[134:135] op_sel_hi:[1,0]
	global_store_dwordx4 v156, v[114:117], s[100:101] offset:576
	s_add_u32 s100, s34, 0x10000
	s_addc_u32 s101, s35, 0
	v_pk_mul_f32 v[110:111], v[110:111], v[136:137] op_sel_hi:[1,0]
	v_pk_mul_f32 v[112:113], v[112:113], v[136:137] op_sel_hi:[1,0]
	global_store_dwordx4 v156, v[110:113], s[100:101]
	v_pk_mul_f32 v[106:107], v[106:107], v[136:137] op_sel_hi:[1,0]
	v_pk_mul_f32 v[108:109], v[108:109], v[136:137] op_sel_hi:[1,0]
	global_store_dwordx4 v156, v[106:109], s[100:101] offset:64
	v_pk_mul_f32 v[102:103], v[102:103], v[136:137] op_sel_hi:[1,0]
	v_pk_mul_f32 v[104:105], v[104:105], v[136:137] op_sel_hi:[1,0]
	global_store_dwordx4 v156, v[102:105], s[100:101] offset:512
	v_pk_mul_f32 v[98:99], v[98:99], v[136:137] op_sel_hi:[1,0]
	v_pk_mul_f32 v[100:101], v[100:101], v[136:137] op_sel_hi:[1,0]
	global_store_dwordx4 v156, v[98:101], s[100:101] offset:576
	s_add_u32 s100, s34, 0x20000
	s_addc_u32 s101, s35, 0
	v_pk_mul_f32 v[94:95], v[94:95], v[138:139] op_sel_hi:[1,0]
	v_pk_mul_f32 v[96:97], v[96:97], v[138:139] op_sel_hi:[1,0]
	global_store_dwordx4 v156, v[94:97], s[100:101]
	v_pk_mul_f32 v[90:91], v[90:91], v[138:139] op_sel_hi:[1,0]
	v_pk_mul_f32 v[92:93], v[92:93], v[138:139] op_sel_hi:[1,0]
	global_store_dwordx4 v156, v[90:93], s[100:101] offset:64
	v_pk_mul_f32 v[86:87], v[86:87], v[138:139] op_sel_hi:[1,0]
	v_pk_mul_f32 v[88:89], v[88:89], v[138:139] op_sel_hi:[1,0]
	global_store_dwordx4 v156, v[86:89], s[100:101] offset:512
	v_pk_mul_f32 v[82:83], v[82:83], v[138:139] op_sel_hi:[1,0]
	v_pk_mul_f32 v[84:85], v[84:85], v[138:139] op_sel_hi:[1,0]
	global_store_dwordx4 v156, v[82:85], s[100:101] offset:576
	s_add_u32 s100, s34, 0x30000
	s_addc_u32 s101, s35, 0
	v_pk_mul_f32 v[78:79], v[78:79], v[140:141] op_sel_hi:[1,0]
	v_pk_mul_f32 v[80:81], v[80:81], v[140:141] op_sel_hi:[1,0]
	global_store_dwordx4 v156, v[78:81], s[100:101]
	v_pk_mul_f32 v[74:75], v[74:75], v[140:141] op_sel_hi:[1,0]
	v_pk_mul_f32 v[76:77], v[76:77], v[140:141] op_sel_hi:[1,0]
	global_store_dwordx4 v156, v[74:77], s[100:101] offset:64
	v_pk_mul_f32 v[70:71], v[70:71], v[140:141] op_sel_hi:[1,0]
	v_pk_mul_f32 v[72:73], v[72:73], v[140:141] op_sel_hi:[1,0]
	global_store_dwordx4 v156, v[70:73], s[100:101] offset:512
	v_pk_mul_f32 v[66:67], v[66:67], v[140:141] op_sel_hi:[1,0]
	v_pk_mul_f32 v[68:69], v[68:69], v[140:141] op_sel_hi:[1,0]
	global_store_dwordx4 v156, v[66:69], s[100:101] offset:576
	s_add_u32 s100, s34, 0x80000
	s_addc_u32 s101, s35, 0
	v_pk_mul_f32 v[62:63], v[62:63], v[142:143] op_sel_hi:[1,0]
	v_pk_mul_f32 v[64:65], v[64:65], v[142:143] op_sel_hi:[1,0]
	global_store_dwordx4 v156, v[62:65], s[100:101]
	v_pk_mul_f32 v[58:59], v[58:59], v[142:143] op_sel_hi:[1,0]
	v_pk_mul_f32 v[60:61], v[60:61], v[142:143] op_sel_hi:[1,0]
	global_store_dwordx4 v156, v[58:61], s[100:101] offset:64
	v_pk_mul_f32 v[54:55], v[54:55], v[142:143] op_sel_hi:[1,0]
	v_pk_mul_f32 v[56:57], v[56:57], v[142:143] op_sel_hi:[1,0]
	global_store_dwordx4 v156, v[54:57], s[100:101] offset:512
	v_pk_mul_f32 v[50:51], v[50:51], v[142:143] op_sel_hi:[1,0]
	v_pk_mul_f32 v[52:53], v[52:53], v[142:143] op_sel_hi:[1,0]
	global_store_dwordx4 v156, v[50:53], s[100:101] offset:576
	s_add_u32 s100, s34, 0x90000
	s_addc_u32 s101, s35, 0
	v_pk_mul_f32 v[46:47], v[46:47], v[146:147] op_sel_hi:[1,0]
	v_pk_mul_f32 v[48:49], v[48:49], v[146:147] op_sel_hi:[1,0]
	global_store_dwordx4 v156, v[46:49], s[100:101]
	v_pk_mul_f32 v[42:43], v[42:43], v[146:147] op_sel_hi:[1,0]
	v_pk_mul_f32 v[44:45], v[44:45], v[146:147] op_sel_hi:[1,0]
	global_store_dwordx4 v156, v[42:45], s[100:101] offset:64
	v_pk_mul_f32 v[38:39], v[38:39], v[146:147] op_sel_hi:[1,0]
	v_pk_mul_f32 v[40:41], v[40:41], v[146:147] op_sel_hi:[1,0]
	global_store_dwordx4 v156, v[38:41], s[100:101] offset:512
	v_pk_mul_f32 v[34:35], v[34:35], v[146:147] op_sel_hi:[1,0]
	v_pk_mul_f32 v[36:37], v[36:37], v[146:147] op_sel_hi:[1,0]
	global_store_dwordx4 v156, v[34:37], s[100:101] offset:576
	s_add_u32 s100, s34, 0xa0000
	s_addc_u32 s101, s35, 0
	v_pk_mul_f32 v[30:31], v[30:31], v[150:151] op_sel_hi:[1,0]
	v_pk_mul_f32 v[32:33], v[32:33], v[150:151] op_sel_hi:[1,0]
	global_store_dwordx4 v156, v[30:33], s[100:101]
	v_pk_mul_f32 v[26:27], v[26:27], v[150:151] op_sel_hi:[1,0]
	v_pk_mul_f32 v[28:29], v[28:29], v[150:151] op_sel_hi:[1,0]
	global_store_dwordx4 v156, v[26:29], s[100:101] offset:64
	v_pk_mul_f32 v[22:23], v[22:23], v[150:151] op_sel_hi:[1,0]
	v_pk_mul_f32 v[24:25], v[24:25], v[150:151] op_sel_hi:[1,0]
	global_store_dwordx4 v156, v[22:25], s[100:101] offset:512
	v_pk_mul_f32 v[18:19], v[18:19], v[150:151] op_sel_hi:[1,0]
	v_pk_mul_f32 v[20:21], v[20:21], v[150:151] op_sel_hi:[1,0]
	global_store_dwordx4 v156, v[18:21], s[100:101] offset:576
	s_add_u32 s100, s34, 0xb0000
	s_addc_u32 s101, s35, 0
	v_pk_mul_f32 v[14:15], v[14:15], v[154:155] op_sel_hi:[1,0]
	v_pk_mul_f32 v[16:17], v[16:17], v[154:155] op_sel_hi:[1,0]
	global_store_dwordx4 v156, v[14:17], s[100:101]
	v_pk_mul_f32 v[10:11], v[10:11], v[154:155] op_sel_hi:[1,0]
	v_pk_mul_f32 v[12:13], v[12:13], v[154:155] op_sel_hi:[1,0]
	global_store_dwordx4 v156, v[10:13], s[100:101] offset:64
	v_pk_mul_f32 v[6:7], v[6:7], v[154:155] op_sel_hi:[1,0]
	v_pk_mul_f32 v[8:9], v[8:9], v[154:155] op_sel_hi:[1,0]
	global_store_dwordx4 v156, v[6:9], s[100:101] offset:512
	v_pk_mul_f32 v[2:3], v[2:3], v[154:155] op_sel_hi:[1,0]
	v_pk_mul_f32 v[4:5], v[4:5], v[154:155] op_sel_hi:[1,0]
	global_store_dwordx4 v156, v[2:5], s[100:101] offset:576
	s_branch .Lepe_done
; DI void st_bf16x4(bf16_t* p, f32x4 v) { u32x2 o; o.x = pk2e(v[0], v[1]); o.y = pk2e(v[2], v[3]); *(u32x2*)p = o; }
; DI void st_tr4(bf16_t* p, size_t stride, f32x4 v) { p[0] = f2bf(v[0]); p[stride] = f2bf(v[1]); p[2 * stride] = f2bf(v[2]); p[3 * stride] = f2bf(v[3]); }
;   DI float operator()(int row, int colbase, int fq, f32x4 v0, f32x4 v1) const { one(row, colbase + 4 * fq, v0); one(row, colbase + 16 + 4 * fq, v1); return 0.f; }
;   DI float operator()(int row, int colbase, int fq, f32x4 v0, f32x4 v1) const { one(row, colbase + 4 * fq, v0); one(row, colbase + 16 + 4 * fq, v1); return 0.f; }
;   DI float operator()(int row, int colbase, int fq, f32x4 v0, f32x4 v1) const { one(row, colbase + 4 * fq, v0); one(row, colbase + 16 + 4 * fq, v1); return 0.f; }
;   DI float rowscale(int row) const { const f32x4 a = *(const f32x4*)(ssp_in + (size_t)row * 8), b = *(const f32x4*)(ssp_in + (size_t)row * 8 + 4);
;     return rsqrtf((((a[0] + a[1]) + (a[2] + a[3])) + ((b[0] + b[1]) + (b[2] + b[3]))) * (1.f / D_) + EPS_); }
;   DI void one(int row, int c, f32x4 v) const {
;     const int b = row >> 12, t = row & 4095;
;     if (c < 3072) {
;       const int seg = c >> 10, cc = c & 1023, h = cc >> 7, d = cc & 127;
;       if (seg < 2) st_bf16x4((bf16_t*)(ws + (seg == 0 ? E_FQ : E_FK)) + ((size_t)(b * 8 + h) * T_ + t) * 128 + d, v);
;       else st_tr4((bf16_t*)(ws + E_FVT) + (size_t)(b * 8 + h) * 128 * T_ + (size_t)(t >> 5) * 4096 + d * 32 + ((((t & 31) >> 2) ^ ((d >> 2) & 7)) << 2) + (t & 3), 32, v);
;     } else if (c < 4096) { st_bf16x4((bf16_t*)(ws + E_HQ) + (size_t)row * 1024 + (c - 3072), v);
;     } else if (c < 5120) { *(f32x4*)((float*)(ws + E_HF) + (size_t)row * 1024 + (c - 4096)) = v;
;     } else if (c < 6144) { const int cc = c - 5120, h = cc >> 7, d = cc & 127; st_tr4((bf16_t*)(ws + E_HIT) + (size_t)(b * 8 + h) * 128 * T_ + (size_t)(t >> 5) * 4096 + d * 32 + (t & 31), 32, v);
;     } else if (c < 7168) { st_bf16x4((bf16_t*)(ws + E_HG) + (size_t)row * 1024 + (c - 6144), v);
;     } else if (c < 7176) { *(f32x4*)((float*)(ws + E_FF) + (size_t)row * 8 + (c - 7168)) = v; }
;   }
;   DI float operator()(int row, int colbase, int fq, f32x4 v0, f32x4 v1) const { one(row, colbase + 4 * fq, v0); one(row, colbase + 16 + 4 * fq, v1); return 0.f; }
.Lepe_generic:
	s_nop 0
	v_readlane_b32 s10, v253, 48
	v_readlane_b32 s11, v253, 49
	v_or_b32_e32 v150, s8, v157
	s_movk_i32 s14, 0xbff
	s_waitcnt vmcnt(14)
	v_mov_b32_e32 v154, v162
	v_mov_b32_e32 v155, v166
	v_mov_b32_e32 v166, v163
	v_pk_add_f32 v[162:163], v[154:155], v[166:167]
	v_mov_b32_e32 v166, v164
	v_mov_b32_e32 v167, v168
	v_mov_b32_e32 v168, v165
	v_pk_add_f32 v[164:165], v[166:167], v[168:169]
	v_lshl_add_u64 v[138:139], s[10:11], 0, v[144:145]
	v_pk_add_f32 v[162:163], v[162:163], v[164:165]
	s_movk_i32 s10, 0x7e0
	v_add_f32_e32 v0, v162, v163
	v_fmamk_f32 v0, v0, 0x3a000000, v249
	v_cmp_gt_f32_e32 vcc, s84, v0
	v_mul_f32_e32 v134, 0x4b800000, v0
	v_mad_i64_i32 v[136:137], s[10:11], v146, s10, v[138:139]
	v_cndmask_b32_e32 v0, v0, v134, vcc
	v_rsq_f32_e32 v0, v0
	s_lshl_b32 s10, s9, 8
	s_and_b32 s19, s10, 0xfc000
	s_add_u32 s12, s4, s19
	v_mul_f32_e32 v134, 0x45800000, v0
	v_cndmask_b32_e32 v142, v0, v134, vcc
	s_addc_u32 s13, s5, 0
	v_lshlrev_b64 v[134:135], 11, v[146:147]
	v_lshl_add_u64 v[140:141], v[136:137], 0, v[134:135]
	s_add_u32 s10, s6, s19
	v_or_b32_e32 v134, s23, v150
	v_mov_b64_e32 v[144:145], s[12:13]
	s_addc_u32 s11, s7, 0
	v_pk_mul_f32 v[128:129], v[128:129], v[142:143] op_sel_hi:[1,0]
	v_pk_mul_f32 v[126:127], v[126:127], v[142:143] op_sel_hi:[1,0]
	v_cmp_lt_i32_e64 s[40:41], s14, v134
	s_and_saveexec_b64 s[14:15], s[40:41]
	s_xor_b64 s[14:15], exec, s[14:15]
	s_cbranch_execz .LBB0_1027
	s_cmpk_gt_u32 s8, 0xfff
	s_mov_b64 s[16:17], -1
	s_cbranch_scc0 .LBB0_1025
	s_cmpk_gt_u32 s8, 0x13ff
	s_cbranch_scc0 .LBB0_1022
	s_cmpk_gt_u32 s8, 0x17ff
	s_cbranch_scc0 .LBB0_1019
	s_cmpk_gt_u32 s8, 0x1bff
	s_cbranch_scc0 .LBB0_1016
	s_movk_i32 s16, 0x1c08
	v_cmp_gt_u32_e32 vcc, s16, v134
	s_and_saveexec_b64 s[16:17], vcc
	s_cbranch_execz .LBB0_1015
	v_mov_b32_e32 v135, v1
	v_lshl_add_u64 v[154:155], v[134:135], 2, v[138:139]
	v_add_co_u32_e32 v154, vcc, 0x3513e000, v154
	s_nop 1
	v_addc_co_u32_e32 v155, vcc, 0, v155, vcc
	global_store_dwordx4 v[154:155], v[126:129], off
